# B2 sliding-window items: runs of read-wait-MFMA triplets now issue all K-fragment LDS reads first into spare quads v232-v243, counted lgkmcnt waits
# baseline (speedup 1.0000x reference)
; DI f32x16 mfma(bf16x8 a, bf16x8 b, f32x16 c) { return __builtin_amdgcn_mfma_f32_32x32x16_bf16(a, b, c, 0, 0, 0); }
; template <int MODE, int KS0, int NKS>
; DI void qk_scores(f32x16& s0, f32x16& s1, const u16* Ks, const bf16x8 (&qf)[4], float sl2, int dl, float mref,
;                   bool need_mask, int r, int h, int rs, const int (&lo)[4]) {
;   asm volatile("" : "+v"(dl));
;   const float nb = -sl2 * (float)dl - mref;
; #pragma unroll
;   for (int i = 0; i < 16; ++i) {
;     const int ci = (i & 3) + 8 * (i >> 2);
;     s0[i] = fmaf(sl2, (float)ci, nb);
;     s1[i] = fmaf(sl2, (float)(ci + 32), nb);
;   }
; #pragma unroll
;   for (int ks = 0; ks < NKS; ++ks) {
;     bf16x8 k0 = ldsv(Ks + lo[KS0 + ks]);
;     bf16x8 k1 = ldsv(Ks + 32 * rs + lo[KS0 + ks]);
;     s0 = mfma(k0, qf[KS0 + ks], s0);
;     s1 = mfma(k1, qf[KS0 + ks], s1);
;   }
;   if (need_mask) {
; #pragma unroll
;     for (int i = 0; i < 16; ++i) {
;       const int ci = (i & 3) + 8 * (i >> 2);
;       bool v0 = (MODE == 0) ? (ci <= dl) : (ci <= dl && ci > dl - 128);
;       bool v1 = (MODE == 0) ? (ci + 32 <= dl) : (ci + 32 <= dl && ci + 32 > dl - 128);
;       s0[i] = v0 ? s0[i] : -INFINITY;
;       s1[i] = v1 ? s1[i] : -INFINITY;
;     }
;   }
; }
; template <int MODE, int KS0, int NKS>
; DI void softmax_pv(const bf16x8 (&qf)[4], const u16* Ks, const u16* Vs, float& m, f32x16& ls, f32x16& o0, f32x16& o1,
;                    float sl2, int dl, bool need_mask, bool first, int r, int h, int rs, const int (&lo)[4]) {
;   f32x16 s0, s1;
;   qk_scores<MODE, KS0, NKS>(s0, s1, Ks, qf, sl2, dl, m, need_mask, r, h, rs, lo);
;   if (__any(first || !(ls[0] <= 1.0e12f))) {
.LBB0_305:
	s_or_b64 exec, exec, s[4:5]
	v_subrev_u32_e32 v217, 64, v184
	v_or_b32_e32 v218, 63, v217
	s_and_saveexec_b64 s[4:5], s[36:37]
	s_cbranch_execz .LBB0_311
	v_cmp_le_i32_e32 vcc, v217, v210
	v_cmp_ge_i32_e64 s[2:3], v218, v211
	s_and_b64 s[6:7], vcc, s[2:3]
	s_and_saveexec_b64 s[2:3], s[6:7]
	s_cbranch_execz .LBB0_310
	v_sub_u32_e32 v82, v214, v184
	v_add3_u32 v230, v82, v208, 64
	s_mov_b32 s6, 2.0
	v_cvt_f32_i32_e32 v82, v230
	s_mov_b32 s7, 0x40400000
	v_lshlrev_b32_e32 v209, 1, v159
	ds_read_b128 v[98:101], v209 offset:18432
	v_fma_f32 v226, -v186, v82, -v220
	v_fma_f32 v84, v186, s6, v226
	v_fma_f32 v85, v186, s7, v226
	s_mov_b32 s6, 0x41000000
	s_mov_b32 s7, 0x41100000
	v_fma_f32 v86, v186, s6, v226
	v_fma_f32 v87, v186, s7, v226
	s_mov_b32 s6, 0x41200000
	s_mov_b32 s7, 0x41300000
	v_fma_f32 v88, v186, s6, v226
	v_fma_f32 v89, v186, s7, v226
	s_mov_b32 s6, 0x41800000
	ds_read_b128 v[222:225], v209 offset:23040
	s_mov_b32 s7, 0x41880000
	v_fma_f32 v90, v186, s6, v226
	v_fma_f32 v91, v186, s7, v226
	s_mov_b32 s6, 0x41900000
	s_mov_b32 s7, 0x41980000
	v_fma_f32 v92, v186, s6, v226
	v_fma_f32 v93, v186, s7, v226
	s_mov_b32 s6, 0x42680000
	s_mov_b32 s7, 0x426c0000
	v_fma_f32 v112, v186, s6, v226
	v_fma_f32 v113, v186, s7, v226
	s_mov_b32 s6, 0x42400000
	v_fma_f32 v82, 0, v186, v226
	v_add_f32_e32 v83, v186, v226
	v_fma_f32 v94, v186, s50, v226
	v_fma_f32 v95, v186, s51, v226
	v_fma_f32 v96, v186, s28, v226
	v_fma_f32 v97, v186, s29, v226
	s_mov_b32 s7, 0x42440000
	v_fma_f32 v110, v186, s30, v226
	v_fma_f32 v111, v186, s31, v226
	s_waitcnt lgkmcnt(1)
	v_mfma_f32_32x32x16_bf16 v[82:97], v[98:101], v[126:129], v[82:97]
	v_fma_f32 v108, v186, s10, v226
	v_fma_f32 v109, v186, s11, v226
	v_fma_f32 v106, v186, s6, v226
	v_fma_f32 v107, v186, s7, v226
	v_fma_f32 v104, v186, s72, v226
	v_fma_f32 v105, v186, s73, v226
	v_fma_f32 v102, v186, s74, v226
	v_fma_f32 v103, v186, s75, v226
	v_fma_f32 v100, v186, s76, v226
	v_fma_f32 v101, v186, s77, v226
	v_fma_f32 v98, v186, s78, v226
	v_fma_f32 v99, v186, s79, v226
	v_add_u32_e32 v215, -1, v230
	v_cmp_gt_u32_e32 vcc, s95, v215
	s_waitcnt lgkmcnt(0)
	v_mfma_f32_32x32x16_bf16 v[98:113], v[222:225], v[126:129], v[98:113]
	ds_read_b128 v[222:225], v209 offset:18464
	v_subrev_u32_e32 v215, 33, v230
	v_subrev_u32_e32 v221, 32, v230
	s_waitcnt lgkmcnt(0)
	v_mfma_f32_32x32x16_bf16 v[82:97], v[222:225], v[122:125], v[82:97]
	ds_read_b128 v[232:235], v209 offset:23072
	ds_read_b128 v[236:239], v209 offset:18496
	ds_read_b128 v[222:225], v209 offset:23104
	s_waitcnt lgkmcnt(2)
	v_mfma_f32_32x32x16_bf16 v[98:113], v[232:235], v[122:125], v[98:113]
	s_waitcnt lgkmcnt(1)
	v_mfma_f32_32x32x16_bf16 v[82:97], v[236:239], v[118:121], v[82:97]
	s_waitcnt lgkmcnt(0)
	v_mfma_f32_32x32x16_bf16 v[98:113], v[222:225], v[118:121], v[98:113]
	ds_read_b128 v[222:225], v209 offset:18528
	ds_read_b128 v[226:229], v209 offset:23136
	s_waitcnt lgkmcnt(1)
	v_mfma_f32_32x32x16_bf16 v[82:97], v[222:225], v[114:117], v[82:97]
	s_waitcnt lgkmcnt(0)
	v_mfma_f32_32x32x16_bf16 v[98:113], v[226:229], v[114:117], v[98:113]
	s_nop 9
	v_cndmask_b32_e32 v83, v199, v83, vcc
	v_cmp_gt_u32_e32 vcc, s95, v230
	s_nop 1
	v_cndmask_b32_e32 v82, v199, v82, vcc
	v_cmp_gt_u32_e32 vcc, s95, v215
	s_nop 1
	v_cndmask_b32_e32 v99, v199, v99, vcc
	v_cmp_gt_u32_e32 vcc, s95, v221
	v_add_u32_e32 v221, -2, v230
	s_nop 0
	v_cndmask_b32_e32 v215, v199, v98, vcc
	v_add_u32_e32 v98, -3, v230
	v_cmp_gt_u32_e32 vcc, s95, v98
	v_subrev_u32_e32 v98, 35, v230
	s_nop 0
	v_cndmask_b32_e32 v85, v199, v85, vcc
	v_cmp_gt_u32_e32 vcc, s95, v221
	v_subrev_u32_e32 v221, 34, v230
	s_nop 0
	v_cndmask_b32_e32 v84, v199, v84, vcc
	v_cmp_gt_u32_e32 vcc, s95, v98
	s_nop 1
	v_cndmask_b32_e32 v98, v199, v101, vcc
	v_cmp_gt_u32_e32 vcc, s95, v221
	v_add_u32_e32 v221, -8, v230
	s_nop 0
	v_cndmask_b32_e32 v101, v199, v100, vcc
	v_add_u32_e32 v100, -9, v230
	v_cmp_gt_u32_e32 vcc, s95, v100
	s_nop 1
	v_cndmask_b32_e32 v222, v199, v87, vcc
	v_cmp_gt_u32_e32 vcc, s95, v221
	v_subrev_u32_e32 v87, 40, v230
	s_nop 0
	v_cndmask_b32_e32 v223, v199, v86, vcc
	v_subrev_u32_e32 v86, 41, v230
	v_cmp_gt_u32_e32 vcc, s95, v86
	v_add_u32_e32 v86, -11, v230
	s_nop 0
	v_cndmask_b32_e32 v100, v199, v103, vcc
	v_cmp_gt_u32_e32 vcc, s95, v87
	v_add_u32_e32 v87, -10, v230
	s_nop 0
	v_cndmask_b32_e32 v102, v199, v102, vcc
	v_cmp_gt_u32_e32 vcc, s95, v86
	v_subrev_u32_e32 v86, 43, v230
	s_nop 0
	v_cndmask_b32_e32 v224, v199, v89, vcc
	v_cmp_gt_u32_e32 vcc, s95, v87
	v_subrev_u32_e32 v87, 42, v230
	v_subrev_u32_e32 v89, 18, v230
	v_cndmask_b32_e32 v225, v199, v88, vcc
	v_cmp_gt_u32_e32 vcc, s95, v86
	v_subrev_u32_e32 v86, 17, v230
	v_subrev_u32_e32 v88, 19, v230
	v_cndmask_b32_e32 v103, v199, v105, vcc
	v_cmp_gt_u32_e32 vcc, s95, v87
	v_add_u32_e32 v87, -16, v230
	s_nop 0
	v_cndmask_b32_e32 v104, v199, v104, vcc
	v_cmp_gt_u32_e32 vcc, s95, v86
	v_subrev_u32_e32 v86, 49, v230
	s_nop 0
	v_cndmask_b32_e32 v105, v199, v91, vcc
	v_cmp_gt_u32_e32 vcc, s95, v87
	v_subrev_u32_e32 v87, 48, v230
	v_subrev_u32_e32 v91, 24, v230
	v_cndmask_b32_e32 v221, v199, v90, vcc
	v_cmp_gt_u32_e32 vcc, s95, v86
	v_subrev_u32_e32 v90, 25, v230
	s_nop 0
	v_cndmask_b32_e32 v86, v199, v107, vcc
	v_cmp_gt_u32_e32 vcc, s95, v87
	s_nop 1
	v_cndmask_b32_e32 v87, v199, v106, vcc
	v_cmp_gt_u32_e32 vcc, s95, v88
	v_subrev_u32_e32 v88, 51, v230
	s_nop 0
	v_cndmask_b32_e32 v106, v199, v93, vcc
	v_cmp_gt_u32_e32 vcc, s95, v89
	v_subrev_u32_e32 v89, 50, v230
	v_subrev_u32_e32 v93, 26, v230
	v_cndmask_b32_e32 v107, v199, v92, vcc
	v_cmp_gt_u32_e32 vcc, s95, v88
	v_subrev_u32_e32 v92, 27, v230
	s_nop 0
	v_cndmask_b32_e32 v88, v199, v109, vcc
	v_cmp_gt_u32_e32 vcc, s95, v89
	s_nop 1
	v_cndmask_b32_e32 v89, v199, v108, vcc
	v_cmp_gt_u32_e32 vcc, s95, v90
	v_subrev_u32_e32 v90, 57, v230
	s_nop 0
	v_cndmask_b32_e32 v95, v199, v95, vcc
	v_cmp_gt_u32_e32 vcc, s95, v91
	v_subrev_u32_e32 v91, 56, v230
	s_nop 0
	v_cndmask_b32_e32 v94, v199, v94, vcc
	v_cmp_gt_u32_e32 vcc, s95, v90
	s_nop 1
	v_cndmask_b32_e32 v90, v199, v111, vcc
	v_cmp_gt_u32_e32 vcc, s95, v91
	s_nop 1
	v_cndmask_b32_e32 v91, v199, v110, vcc
	v_cmp_gt_u32_e32 vcc, s95, v92
	v_subrev_u32_e32 v92, 59, v230
	s_nop 0
	v_cndmask_b32_e32 v97, v199, v97, vcc
	v_cmp_gt_u32_e32 vcc, s95, v93
	v_subrev_u32_e32 v93, 58, v230
	s_nop 0
	v_cndmask_b32_e32 v96, v199, v96, vcc
	v_cmp_gt_u32_e32 vcc, s95, v92
	s_nop 1
	v_cndmask_b32_e32 v92, v199, v113, vcc
	v_cmp_gt_u32_e32 vcc, s95, v93
	s_nop 1
	v_cndmask_b32_e32 v93, v199, v112, vcc
	v_cmp_nge_f32_e32 vcc, s9, v50
	s_cbranch_vccz .LBB0_309
; DI float ex2(float x) { return __builtin_amdgcn_exp2f(x); }
; DI float lg2(float x) { return __builtin_amdgcn_logf(x); }
; template <int MODE, int KS0, int NKS>
; DI void softmax_pv(const bf16x8 (&qf)[4], const u16* Ks, const u16* Vs, float& m, f32x16& ls, f32x16& o0, f32x16& o1,
;                    float sl2, int dl, bool need_mask, bool first, int r, int h, int rs, const int (&lo)[4]) {
;     ...
;   if (__any(first || !(ls[0] <= 1.0e12f))) {
;     float tmax = -INFINITY;
; #pragma unroll
;     for (int i = 0; i < 16; ++i) tmax = fmaxf(tmax, fmaxf(s0[i], s1[i]));
;     tmax = fmaxf(tmax, shx(tmax, r + 32 * h));
;     const float lref = (ls[0] > 1.f) ? lg2(ls[0]) : 0.f;
;     const float delta = first ? tmax : fmaxf(fmaxf(tmax, lref), 0.f);
;     m += delta;
;     const float alpha = ex2(-delta);
; #pragma unroll
;     for (int e = 0; e < 16; ++e) { o0[e] *= alpha; o1[e] *= alpha; ls[e] *= alpha; }
; #pragma unroll
;     for (int i = 0; i < 16; ++i) { s0[i] -= delta; s1[i] -= delta; }
;   }
	v_max_f32_e32 v108, v215, v215
	v_max_f32_e32 v109, v82, v82
	v_max_f32_e32 v108, v109, v108
	v_max_f32_e32 v109, v99, v99
	v_max_f32_e32 v110, v83, v83
	v_max_f32_e32 v109, v110, v109
	s_mov_b32 s6, 0xff800000
	v_max3_f32 v108, v108, s6, v109
	v_max_f32_e32 v109, v101, v101
	v_max_f32_e32 v110, v84, v84
	v_max_f32_e32 v109, v110, v109
	v_max_f32_e32 v110, v98, v98
	v_max_f32_e32 v111, v85, v85
	v_max_f32_e32 v110, v111, v110
	v_max3_f32 v108, v108, v109, v110
	v_max_f32_e32 v109, v102, v102
	v_max_f32_e32 v110, v223, v223
	v_max_f32_e32 v109, v110, v109
	v_max_f32_e32 v110, v100, v100
	v_max_f32_e32 v111, v222, v222
	v_max_f32_e32 v110, v111, v110
	v_max3_f32 v108, v108, v109, v110
	v_max_f32_e32 v109, v104, v104
	v_max_f32_e32 v110, v225, v225
	v_max_f32_e32 v109, v110, v109
	v_max_f32_e32 v110, v103, v103
	v_max_f32_e32 v111, v224, v224
	v_max_f32_e32 v110, v111, v110
	v_max3_f32 v108, v108, v109, v110
	v_max_f32_e32 v109, v87, v87
	v_max_f32_e32 v110, v221, v221
	v_max_f32_e32 v109, v110, v109
	v_max_f32_e32 v110, v86, v86
	v_max_f32_e32 v111, v105, v105
	v_max_f32_e32 v110, v111, v110
	v_max3_f32 v108, v108, v109, v110
	v_max_f32_e32 v109, v89, v89
	v_max_f32_e32 v110, v107, v107
	v_max_f32_e32 v109, v110, v109
	v_max_f32_e32 v110, v88, v88
	v_max_f32_e32 v111, v106, v106
	v_max_f32_e32 v110, v111, v110
	v_max3_f32 v108, v108, v109, v110
	v_max_f32_e32 v109, v91, v91
	v_max_f32_e32 v110, v94, v94
	v_max_f32_e32 v109, v110, v109
	v_max_f32_e32 v110, v90, v90
	v_max_f32_e32 v111, v95, v95
	v_max_f32_e32 v110, v111, v110
	v_max3_f32 v108, v108, v109, v110
	v_max_f32_e32 v109, v93, v93
	v_max_f32_e32 v110, v96, v96
	v_max_f32_e32 v109, v110, v109
	v_max_f32_e32 v110, v92, v92
	v_max_f32_e32 v111, v97, v97
	v_max_f32_e32 v110, v111, v110
	v_max3_f32 v108, v108, v109, v110
	ds_bpermute_b32 v109, v185, v108
	v_log_f32_e32 v110, v50
	v_cmp_lt_f32_e32 vcc, 1.0, v50
	s_waitcnt lgkmcnt(0)
	v_max_f32_e32 v109, v109, v109
	v_max_f32_e32 v108, v108, v109
	v_cndmask_b32_e32 v109, 0, v110, vcc
	v_max3_f32 v109, v108, v109, 0
	v_exp_f32_e64 v108, -v109
	v_add_f32_e32 v220, v220, v109
	v_sub_f32_e32 v82, v82, v109
	v_sub_f32_e32 v83, v83, v109
	v_mul_f32_e32 v80, v80, v108
	v_mul_f32_e32 v81, v81, v108
	v_mul_f32_e32 v78, v78, v108
	v_mul_f32_e32 v79, v79, v108
	v_mul_f32_e32 v76, v76, v108
	v_mul_f32_e32 v77, v77, v108
	v_mul_f32_e32 v74, v74, v108
	v_mul_f32_e32 v75, v75, v108
	v_mul_f32_e32 v72, v72, v108
	v_mul_f32_e32 v73, v73, v108
	v_mul_f32_e32 v70, v70, v108
	v_mul_f32_e32 v71, v71, v108
	v_mul_f32_e32 v68, v68, v108
	v_mul_f32_e32 v69, v69, v108
	v_mul_f32_e32 v66, v66, v108
	v_mul_f32_e32 v67, v67, v108
	v_mul_f32_e32 v48, v48, v108
	v_mul_f32_e32 v49, v49, v108
	v_mul_f32_e32 v46, v46, v108
	v_mul_f32_e32 v47, v47, v108
	v_mul_f32_e32 v44, v44, v108
	v_mul_f32_e32 v45, v45, v108
	v_mul_f32_e32 v42, v42, v108
	v_mul_f32_e32 v43, v43, v108
	v_mul_f32_e32 v40, v40, v108
	v_mul_f32_e32 v41, v41, v108
	v_mul_f32_e32 v38, v38, v108
	v_mul_f32_e32 v39, v39, v108
	v_mul_f32_e32 v36, v36, v108
	v_mul_f32_e32 v37, v37, v108
	v_mul_f32_e32 v34, v34, v108
	v_mul_f32_e32 v35, v35, v108
	v_mul_f32_e32 v64, v64, v108
	v_mul_f32_e32 v65, v65, v108
	v_mul_f32_e32 v62, v62, v108
	v_mul_f32_e32 v63, v63, v108
	v_mul_f32_e32 v60, v60, v108
	v_mul_f32_e32 v61, v61, v108
	v_mul_f32_e32 v58, v58, v108
	v_mul_f32_e32 v59, v59, v108
	v_mul_f32_e32 v56, v56, v108
	v_mul_f32_e32 v57, v57, v108
	v_mul_f32_e32 v54, v54, v108
	v_mul_f32_e32 v55, v55, v108
	v_mul_f32_e32 v52, v52, v108
	v_mul_f32_e32 v53, v53, v108
	v_mul_f32_e32 v50, v50, v108
	v_mul_f32_e32 v51, v51, v108
	v_sub_f32_e32 v84, v84, v109
	v_sub_f32_e32 v85, v85, v109
	v_sub_f32_e32 v223, v223, v109
	v_sub_f32_e32 v222, v222, v109
	v_sub_f32_e32 v225, v225, v109
	v_sub_f32_e32 v224, v224, v109
	v_sub_f32_e32 v221, v221, v109
	v_sub_f32_e32 v105, v105, v109
	v_sub_f32_e32 v107, v107, v109
	v_sub_f32_e32 v106, v106, v109
	v_sub_f32_e32 v94, v94, v109
	v_sub_f32_e32 v95, v95, v109
	v_sub_f32_e32 v96, v96, v109
	v_sub_f32_e32 v97, v97, v109
	v_sub_f32_e32 v215, v215, v109
	v_sub_f32_e32 v99, v99, v109
	v_sub_f32_e32 v101, v101, v109
	v_sub_f32_e32 v98, v98, v109
	v_sub_f32_e32 v102, v102, v109
	v_sub_f32_e32 v100, v100, v109
	v_sub_f32_e32 v104, v104, v109
	v_sub_f32_e32 v103, v103, v109
	v_sub_f32_e32 v87, v87, v109
	v_sub_f32_e32 v86, v86, v109
	v_sub_f32_e32 v89, v89, v109
	v_sub_f32_e32 v88, v88, v109
	v_sub_f32_e32 v91, v91, v109
	v_sub_f32_e32 v90, v90, v109
	v_sub_f32_e32 v93, v93, v109
	v_sub_f32_e32 v92, v92, v109

; DI f32x16 mfma(bf16x8 a, bf16x8 b, f32x16 c) { return __builtin_amdgcn_mfma_f32_32x32x16_bf16(a, b, c, 0, 0, 0); }
; template <int MODE, int KS0, int NKS>
; DI void qk_scores(f32x16& s0, f32x16& s1, const u16* Ks, const bf16x8 (&qf)[4], float sl2, int dl, float mref,
;                   bool need_mask, int r, int h, int rs, const int (&lo)[4]) {
;   asm volatile("" : "+v"(dl));
;   const float nb = -sl2 * (float)dl - mref;
; #pragma unroll
;   for (int i = 0; i < 16; ++i) {
;     const int ci = (i & 3) + 8 * (i >> 2);
;     s0[i] = fmaf(sl2, (float)ci, nb);
;     s1[i] = fmaf(sl2, (float)(ci + 32), nb);
;   }
; #pragma unroll
;   for (int ks = 0; ks < NKS; ++ks) {
;     bf16x8 k0 = ldsv(Ks + lo[KS0 + ks]);
;     bf16x8 k1 = ldsv(Ks + 32 * rs + lo[KS0 + ks]);
;     s0 = mfma(k0, qf[KS0 + ks], s0);
;     s1 = mfma(k1, qf[KS0 + ks], s1);
;   }
;   if (need_mask) {
; #pragma unroll
;     for (int i = 0; i < 16; ++i) {
;       const int ci = (i & 3) + 8 * (i >> 2);
;       bool v0 = (MODE == 0) ? (ci <= dl) : (ci <= dl && ci > dl - 128);
;       bool v1 = (MODE == 0) ? (ci + 32 <= dl) : (ci + 32 <= dl && ci + 32 > dl - 128);
;       s0[i] = v0 ? s0[i] : -INFINITY;
;       s1[i] = v1 ? s1[i] : -INFINITY;
;     }
;   }
; }
; template <int MODE, int KS0, int NKS>
; DI void softmax_pv(const bf16x8 (&qf)[4], const u16* Ks, const u16* Vs, float& m, f32x16& ls, f32x16& o0, f32x16& o1,
;                    float sl2, int dl, bool need_mask, bool first, int r, int h, int rs, const int (&lo)[4]) {
;   f32x16 s0, s1;
;   qk_scores<MODE, KS0, NKS>(s0, s1, Ks, qf, sl2, dl, m, need_mask, r, h, rs, lo);
;   if (__any(first || !(ls[0] <= 1.0e12f))) {
.LBB0_311:
	s_or_b64 exec, exec, s[4:5]
	v_or_b32_e32 v82, 63, v184
	v_cmp_le_i32_e32 vcc, v184, v210
	v_cmp_ge_i32_e64 s[2:3], v82, v211
	v_sub_u32_e32 v221, v214, v184
	s_and_b64 s[4:5], vcc, s[2:3]
	v_lshlrev_b32_e32 v209, 1, v159
	v_add_u32_e32 v215, v221, v208
	s_and_saveexec_b64 s[2:3], s[4:5]
	s_cbranch_execz .LBB0_315
	v_mov_b32_e32 v230, v215
	s_mov_b32 s6, 2.0
	v_cvt_f32_i32_e32 v82, v230
	s_mov_b32 s7, 0x40400000
	ds_read_b128 v[98:101], v209 offset:36864
	ds_read_b128 v[222:225], v209 offset:41472
	v_fma_f32 v226, -v186, v82, -v220
	v_fma_f32 v84, v186, s6, v226
	v_fma_f32 v85, v186, s7, v226
	s_mov_b32 s6, 0x41000000
	s_mov_b32 s7, 0x41100000
	v_fma_f32 v86, v186, s6, v226
	v_fma_f32 v87, v186, s7, v226
	s_mov_b32 s6, 0x41200000
	s_mov_b32 s7, 0x41300000
	v_fma_f32 v88, v186, s6, v226
	v_fma_f32 v89, v186, s7, v226
	s_mov_b32 s6, 0x41800000
	s_mov_b32 s7, 0x41880000
	v_fma_f32 v90, v186, s6, v226
	v_fma_f32 v91, v186, s7, v226
	s_mov_b32 s6, 0x41900000
	s_mov_b32 s7, 0x41980000
	v_fma_f32 v92, v186, s6, v226
	v_fma_f32 v93, v186, s7, v226
	s_mov_b32 s6, 0x42680000
	s_mov_b32 s7, 0x426c0000
	v_fma_f32 v112, v186, s6, v226
	v_fma_f32 v113, v186, s7, v226
	s_mov_b32 s6, 0x42400000
	v_fma_f32 v82, 0, v186, v226
	v_add_f32_e32 v83, v186, v226
	v_fma_f32 v94, v186, s50, v226
	v_fma_f32 v95, v186, s51, v226
	v_fma_f32 v96, v186, s28, v226
	v_fma_f32 v97, v186, s29, v226
	s_mov_b32 s7, 0x42440000
	v_fma_f32 v110, v186, s30, v226
	v_fma_f32 v111, v186, s31, v226
	s_waitcnt lgkmcnt(1)
	v_mfma_f32_32x32x16_bf16 v[82:97], v[98:101], v[126:129], v[82:97]
	v_fma_f32 v108, v186, s10, v226
	v_fma_f32 v109, v186, s11, v226
	v_fma_f32 v106, v186, s6, v226
	v_fma_f32 v107, v186, s7, v226
	v_fma_f32 v104, v186, s72, v226
	v_fma_f32 v105, v186, s73, v226
	v_fma_f32 v102, v186, s74, v226
	v_fma_f32 v103, v186, s75, v226
	v_fma_f32 v100, v186, s76, v226
	v_fma_f32 v101, v186, s77, v226
	v_fma_f32 v98, v186, s78, v226
	v_fma_f32 v99, v186, s79, v226
	v_add_u32_e32 v231, -1, v230
	v_cmp_gt_u32_e32 vcc, s95, v231
	s_waitcnt lgkmcnt(0)
	v_mfma_f32_32x32x16_bf16 v[98:113], v[222:225], v[126:129], v[98:113]
	ds_read_b128 v[232:235], v209 offset:36896
	ds_read_b128 v[236:239], v209 offset:41504
	ds_read_b128 v[240:243], v209 offset:36928
	ds_read_b128 v[222:225], v209 offset:41536
	s_waitcnt lgkmcnt(3)
	v_mfma_f32_32x32x16_bf16 v[82:97], v[232:235], v[122:125], v[82:97]
	s_waitcnt lgkmcnt(2)
	v_mfma_f32_32x32x16_bf16 v[98:113], v[236:239], v[122:125], v[98:113]
	s_waitcnt lgkmcnt(1)
	v_mfma_f32_32x32x16_bf16 v[82:97], v[240:243], v[118:121], v[82:97]
	s_waitcnt lgkmcnt(0)
	v_mfma_f32_32x32x16_bf16 v[98:113], v[222:225], v[118:121], v[98:113]
	ds_read_b128 v[222:225], v209 offset:36960
	ds_read_b128 v[226:229], v209 offset:41568
	s_waitcnt lgkmcnt(1)
	v_mfma_f32_32x32x16_bf16 v[82:97], v[222:225], v[114:117], v[82:97]
	v_subrev_u32_e32 v222, 33, v230
	v_subrev_u32_e32 v223, 32, v230
	s_waitcnt lgkmcnt(0)
	v_mfma_f32_32x32x16_bf16 v[98:113], v[226:229], v[114:117], v[98:113]
	s_nop 7
	v_cndmask_b32_e32 v83, v199, v83, vcc
	v_cmp_gt_u32_e32 vcc, s95, v230
	s_nop 1
	v_cndmask_b32_e32 v82, v199, v82, vcc
	v_cmp_gt_u32_e32 vcc, s95, v222
	s_nop 1
	v_cndmask_b32_e32 v99, v199, v99, vcc
	v_cmp_gt_u32_e32 vcc, s95, v223
	v_add_u32_e32 v223, -2, v230
	s_nop 0
	v_cndmask_b32_e32 v222, v199, v98, vcc
	v_add_u32_e32 v98, -3, v230
	v_cmp_gt_u32_e32 vcc, s95, v98
	v_subrev_u32_e32 v98, 35, v230
	s_nop 0
	v_cndmask_b32_e32 v85, v199, v85, vcc
	v_cmp_gt_u32_e32 vcc, s95, v223
	v_subrev_u32_e32 v223, 34, v230
	s_nop 0
	v_cndmask_b32_e32 v84, v199, v84, vcc
	v_cmp_gt_u32_e32 vcc, s95, v98
	s_nop 1
	v_cndmask_b32_e32 v98, v199, v101, vcc
	v_cmp_gt_u32_e32 vcc, s95, v223
	v_add_u32_e32 v223, -8, v230
	s_nop 0
	v_cndmask_b32_e32 v101, v199, v100, vcc
	v_add_u32_e32 v100, -9, v230
	v_cmp_gt_u32_e32 vcc, s95, v100
	s_nop 1
	v_cndmask_b32_e32 v224, v199, v87, vcc
	v_cmp_gt_u32_e32 vcc, s95, v223
	v_subrev_u32_e32 v87, 40, v230
	s_nop 0
	v_cndmask_b32_e32 v225, v199, v86, vcc
	v_subrev_u32_e32 v86, 41, v230
	v_cmp_gt_u32_e32 vcc, s95, v86
	v_add_u32_e32 v86, -11, v230
	s_nop 0
	v_cndmask_b32_e32 v100, v199, v103, vcc
	v_cmp_gt_u32_e32 vcc, s95, v87
	v_add_u32_e32 v87, -10, v230
	s_nop 0
	v_cndmask_b32_e32 v102, v199, v102, vcc
	v_cmp_gt_u32_e32 vcc, s95, v86
	v_subrev_u32_e32 v86, 43, v230
	s_nop 0
	v_cndmask_b32_e32 v226, v199, v89, vcc
	v_cmp_gt_u32_e32 vcc, s95, v87
	v_subrev_u32_e32 v87, 42, v230
	v_subrev_u32_e32 v89, 18, v230
	v_cndmask_b32_e32 v227, v199, v88, vcc
	v_cmp_gt_u32_e32 vcc, s95, v86
	v_subrev_u32_e32 v86, 17, v230
	v_subrev_u32_e32 v88, 19, v230
	v_cndmask_b32_e32 v103, v199, v105, vcc
	v_cmp_gt_u32_e32 vcc, s95, v87
	v_add_u32_e32 v87, -16, v230
	s_nop 0
	v_cndmask_b32_e32 v104, v199, v104, vcc
	v_cmp_gt_u32_e32 vcc, s95, v86
	v_subrev_u32_e32 v86, 49, v230
	s_nop 0
	v_cndmask_b32_e32 v105, v199, v91, vcc
	v_cmp_gt_u32_e32 vcc, s95, v87
	v_subrev_u32_e32 v87, 48, v230
	v_subrev_u32_e32 v91, 24, v230
	v_cndmask_b32_e32 v223, v199, v90, vcc
	v_cmp_gt_u32_e32 vcc, s95, v86
	v_subrev_u32_e32 v90, 25, v230
	s_nop 0
	v_cndmask_b32_e32 v86, v199, v107, vcc
	v_cmp_gt_u32_e32 vcc, s95, v87
	s_nop 1
	v_cndmask_b32_e32 v87, v199, v106, vcc
	v_cmp_gt_u32_e32 vcc, s95, v88
	v_subrev_u32_e32 v88, 51, v230
	s_nop 0
	v_cndmask_b32_e32 v106, v199, v93, vcc
	v_cmp_gt_u32_e32 vcc, s95, v89
	v_subrev_u32_e32 v89, 50, v230
	v_subrev_u32_e32 v93, 26, v230
	v_cndmask_b32_e32 v107, v199, v92, vcc
	v_cmp_gt_u32_e32 vcc, s95, v88
	v_subrev_u32_e32 v92, 27, v230
	s_nop 0
	v_cndmask_b32_e32 v88, v199, v109, vcc
	v_cmp_gt_u32_e32 vcc, s95, v89
	s_nop 1
	v_cndmask_b32_e32 v89, v199, v108, vcc
	v_cmp_gt_u32_e32 vcc, s95, v90
	v_subrev_u32_e32 v90, 57, v230
	s_nop 0
	v_cndmask_b32_e32 v95, v199, v95, vcc
	v_cmp_gt_u32_e32 vcc, s95, v91
	v_subrev_u32_e32 v91, 56, v230
	s_nop 0
	v_cndmask_b32_e32 v94, v199, v94, vcc
	v_cmp_gt_u32_e32 vcc, s95, v90
	s_nop 1
	v_cndmask_b32_e32 v90, v199, v111, vcc
	v_cmp_gt_u32_e32 vcc, s95, v91
	s_nop 1
	v_cndmask_b32_e32 v91, v199, v110, vcc
	v_cmp_gt_u32_e32 vcc, s95, v92
	v_subrev_u32_e32 v92, 59, v230
	s_nop 0
	v_cndmask_b32_e32 v97, v199, v97, vcc
	v_cmp_gt_u32_e32 vcc, s95, v93
	v_subrev_u32_e32 v93, 58, v230
	s_nop 0
	v_cndmask_b32_e32 v96, v199, v96, vcc
	v_cmp_gt_u32_e32 vcc, s95, v92
	s_nop 1
	v_cndmask_b32_e32 v92, v199, v113, vcc
	v_cmp_gt_u32_e32 vcc, s95, v93
	s_nop 1
	v_cndmask_b32_e32 v93, v199, v112, vcc
	v_cmp_nge_f32_e32 vcc, s9, v50
	s_cbranch_vccz .LBB0_314
; DI float ex2(float x) { return __builtin_amdgcn_exp2f(x); }
; DI float lg2(float x) { return __builtin_amdgcn_logf(x); }
; template <int MODE, int KS0, int NKS>
; DI void softmax_pv(const bf16x8 (&qf)[4], const u16* Ks, const u16* Vs, float& m, f32x16& ls, f32x16& o0, f32x16& o1,
;                    float sl2, int dl, bool need_mask, bool first, int r, int h, int rs, const int (&lo)[4]) {
;     ...
;   if (__any(first || !(ls[0] <= 1.0e12f))) {
;     float tmax = -INFINITY;
; #pragma unroll
;     for (int i = 0; i < 16; ++i) tmax = fmaxf(tmax, fmaxf(s0[i], s1[i]));
;     tmax = fmaxf(tmax, shx(tmax, r + 32 * h));
;     const float lref = (ls[0] > 1.f) ? lg2(ls[0]) : 0.f;
;     const float delta = first ? tmax : fmaxf(fmaxf(tmax, lref), 0.f);
;     m += delta;
;     const float alpha = ex2(-delta);
; #pragma unroll
;     for (int e = 0; e < 16; ++e) { o0[e] *= alpha; o1[e] *= alpha; ls[e] *= alpha; }
; #pragma unroll
;     for (int i = 0; i < 16; ++i) { s0[i] -= delta; s1[i] -= delta; }
;   }
	v_max_f32_e32 v108, v222, v222
	v_max_f32_e32 v109, v82, v82
	v_max_f32_e32 v108, v109, v108
	v_max_f32_e32 v109, v99, v99
	v_max_f32_e32 v110, v83, v83
	v_max_f32_e32 v109, v110, v109
	s_mov_b32 s6, 0xff800000
	v_max3_f32 v108, v108, s6, v109
	v_max_f32_e32 v109, v101, v101
	v_max_f32_e32 v110, v84, v84
	v_max_f32_e32 v109, v110, v109
	v_max_f32_e32 v110, v98, v98
	v_max_f32_e32 v111, v85, v85
	v_max_f32_e32 v110, v111, v110
	v_max3_f32 v108, v108, v109, v110
	v_max_f32_e32 v109, v102, v102
	v_max_f32_e32 v110, v225, v225
	v_max_f32_e32 v109, v110, v109
	v_max_f32_e32 v110, v100, v100
	v_max_f32_e32 v111, v224, v224
	v_max_f32_e32 v110, v111, v110
	v_max3_f32 v108, v108, v109, v110
	v_max_f32_e32 v109, v104, v104
	v_max_f32_e32 v110, v227, v227
	v_max_f32_e32 v109, v110, v109
	v_max_f32_e32 v110, v103, v103
	v_max_f32_e32 v111, v226, v226
	v_max_f32_e32 v110, v111, v110
	v_max3_f32 v108, v108, v109, v110
	v_max_f32_e32 v109, v87, v87
	v_max_f32_e32 v110, v223, v223
	v_max_f32_e32 v109, v110, v109
	v_max_f32_e32 v110, v86, v86
	v_max_f32_e32 v111, v105, v105
	v_max_f32_e32 v110, v111, v110
	v_max3_f32 v108, v108, v109, v110
	v_max_f32_e32 v109, v89, v89
	v_max_f32_e32 v110, v107, v107
	v_max_f32_e32 v109, v110, v109
	v_max_f32_e32 v110, v88, v88
	v_max_f32_e32 v111, v106, v106
	v_max_f32_e32 v110, v111, v110
	v_max3_f32 v108, v108, v109, v110
	v_max_f32_e32 v109, v91, v91
	v_max_f32_e32 v110, v94, v94
	v_max_f32_e32 v109, v110, v109
	v_max_f32_e32 v110, v90, v90
	v_max_f32_e32 v111, v95, v95
	v_max_f32_e32 v110, v111, v110
	v_max3_f32 v108, v108, v109, v110
	v_max_f32_e32 v109, v93, v93
	v_max_f32_e32 v110, v96, v96
	v_max_f32_e32 v109, v110, v109
	v_max_f32_e32 v110, v92, v92
	v_max_f32_e32 v111, v97, v97
	v_max_f32_e32 v110, v111, v110
	v_max3_f32 v108, v108, v109, v110
	ds_bpermute_b32 v109, v185, v108
	v_log_f32_e32 v110, v50
	v_cmp_lt_f32_e32 vcc, 1.0, v50
	s_waitcnt lgkmcnt(0)
	v_max_f32_e32 v109, v109, v109
	v_max_f32_e32 v108, v108, v109
	v_cndmask_b32_e32 v109, 0, v110, vcc
	v_max3_f32 v109, v108, v109, 0
	v_exp_f32_e64 v108, -v109
	v_add_f32_e32 v220, v220, v109
	v_sub_f32_e32 v82, v82, v109
	v_sub_f32_e32 v83, v83, v109
	v_mul_f32_e32 v80, v80, v108
	v_mul_f32_e32 v81, v81, v108
	v_mul_f32_e32 v78, v78, v108
	v_mul_f32_e32 v79, v79, v108
	v_mul_f32_e32 v76, v76, v108
	v_mul_f32_e32 v77, v77, v108
	v_mul_f32_e32 v74, v74, v108
	v_mul_f32_e32 v75, v75, v108
	v_mul_f32_e32 v72, v72, v108
	v_mul_f32_e32 v73, v73, v108
	v_mul_f32_e32 v70, v70, v108
	v_mul_f32_e32 v71, v71, v108
	v_mul_f32_e32 v68, v68, v108
	v_mul_f32_e32 v69, v69, v108
	v_mul_f32_e32 v66, v66, v108
	v_mul_f32_e32 v67, v67, v108
	v_mul_f32_e32 v48, v48, v108
	v_mul_f32_e32 v49, v49, v108
	v_mul_f32_e32 v46, v46, v108
	v_mul_f32_e32 v47, v47, v108
	v_mul_f32_e32 v44, v44, v108
	v_mul_f32_e32 v45, v45, v108
	v_mul_f32_e32 v42, v42, v108
	v_mul_f32_e32 v43, v43, v108
	v_mul_f32_e32 v40, v40, v108
	v_mul_f32_e32 v41, v41, v108
	v_mul_f32_e32 v38, v38, v108
	v_mul_f32_e32 v39, v39, v108
	v_mul_f32_e32 v36, v36, v108
	v_mul_f32_e32 v37, v37, v108
	v_mul_f32_e32 v34, v34, v108
	v_mul_f32_e32 v35, v35, v108
	v_mul_f32_e32 v64, v64, v108
	v_mul_f32_e32 v65, v65, v108
	v_mul_f32_e32 v62, v62, v108
	v_mul_f32_e32 v63, v63, v108
	v_mul_f32_e32 v60, v60, v108
	v_mul_f32_e32 v61, v61, v108
	v_mul_f32_e32 v58, v58, v108
	v_mul_f32_e32 v59, v59, v108
	v_mul_f32_e32 v56, v56, v108
	v_mul_f32_e32 v57, v57, v108
	v_mul_f32_e32 v54, v54, v108
	v_mul_f32_e32 v55, v55, v108
	v_mul_f32_e32 v52, v52, v108
	v_mul_f32_e32 v53, v53, v108
	v_mul_f32_e32 v50, v50, v108
	v_mul_f32_e32 v51, v51, v108
	v_sub_f32_e32 v84, v84, v109
	v_sub_f32_e32 v85, v85, v109
	v_sub_f32_e32 v225, v225, v109
	v_sub_f32_e32 v224, v224, v109
	v_sub_f32_e32 v227, v227, v109
	v_sub_f32_e32 v226, v226, v109
	v_sub_f32_e32 v223, v223, v109
	v_sub_f32_e32 v105, v105, v109
	v_sub_f32_e32 v107, v107, v109
	v_sub_f32_e32 v106, v106, v109
	v_sub_f32_e32 v94, v94, v109
	v_sub_f32_e32 v95, v95, v109
	v_sub_f32_e32 v96, v96, v109
	v_sub_f32_e32 v97, v97, v109
	v_sub_f32_e32 v222, v222, v109
	v_sub_f32_e32 v99, v99, v109
	v_sub_f32_e32 v101, v101, v109
	v_sub_f32_e32 v98, v98, v109
	v_sub_f32_e32 v102, v102, v109
	v_sub_f32_e32 v100, v100, v109
	v_sub_f32_e32 v104, v104, v109
	v_sub_f32_e32 v103, v103, v109
	v_sub_f32_e32 v87, v87, v109
	v_sub_f32_e32 v86, v86, v109
	v_sub_f32_e32 v89, v89, v109
	v_sub_f32_e32 v88, v88, v109
	v_sub_f32_e32 v91, v91, v109
	v_sub_f32_e32 v90, v90, v109
	v_sub_f32_e32 v93, v93, v109
	v_sub_f32_e32 v92, v92, v109

; DI f32x16 mfma(bf16x8 a, bf16x8 b, f32x16 c) { return __builtin_amdgcn_mfma_f32_32x32x16_bf16(a, b, c, 0, 0, 0); }
; template <int MODE, int KS0, int NKS>
; DI void qk_scores(f32x16& s0, f32x16& s1, const u16* Ks, const bf16x8 (&qf)[4], float sl2, int dl, float mref,
;                   bool need_mask, int r, int h, int rs, const int (&lo)[4]) {
;   asm volatile("" : "+v"(dl));
;   const float nb = -sl2 * (float)dl - mref;
; #pragma unroll
;   for (int i = 0; i < 16; ++i) {
;     const int ci = (i & 3) + 8 * (i >> 2);
;     s0[i] = fmaf(sl2, (float)ci, nb);
;     s1[i] = fmaf(sl2, (float)(ci + 32), nb);
;   }
; #pragma unroll
;   for (int ks = 0; ks < NKS; ++ks) {
;     bf16x8 k0 = ldsv(Ks + lo[KS0 + ks]);
;     bf16x8 k1 = ldsv(Ks + 32 * rs + lo[KS0 + ks]);
;     s0 = mfma(k0, qf[KS0 + ks], s0);
;     s1 = mfma(k1, qf[KS0 + ks], s1);
;   }
;   if (need_mask) {
; #pragma unroll
;     for (int i = 0; i < 16; ++i) {
;       const int ci = (i & 3) + 8 * (i >> 2);
;       bool v0 = (MODE == 0) ? (ci <= dl) : (ci <= dl && ci > dl - 128);
;       bool v1 = (MODE == 0) ? (ci + 32 <= dl) : (ci + 32 <= dl && ci + 32 > dl - 128);
;       s0[i] = v0 ? s0[i] : -INFINITY;
;       s1[i] = v1 ? s1[i] : -INFINITY;
;     }
;   }
; }
; template <int MODE, int KS0, int NKS>
; DI void softmax_pv(const bf16x8 (&qf)[4], const u16* Ks, const u16* Vs, float& m, f32x16& ls, f32x16& o0, f32x16& o1,
;                    float sl2, int dl, bool need_mask, bool first, int r, int h, int rs, const int (&lo)[4]) {
;   f32x16 s0, s1;
;   qk_scores<MODE, KS0, NKS>(s0, s1, Ks, qf, sl2, dl, m, need_mask, r, h, rs, lo);
;   if (__any(first || !(ls[0] <= 1.0e12f))) {
.LBB0_315:
	s_or_b64 exec, exec, s[2:3]
	v_or_b32_e32 v82, 0x7f, v184
	v_cmp_le_i32_e32 vcc, v219, v210
	v_cmp_ge_i32_e64 s[2:3], v82, v211
	v_sub_u32_e32 v82, v214, v219
	s_and_b64 s[6:7], vcc, s[2:3]
	v_add_u32_e32 v184, v82, v208
	s_and_saveexec_b64 s[2:3], s[6:7]
	s_cbranch_execz .LBB0_319
	v_mov_b32_e32 v219, v184
	s_mov_b32 s44, 2.0
	v_cvt_f32_i32_e32 v82, v219
	s_mov_b32 s45, 0x40400000
	ds_read_b128 v[98:101], v209 offset:55296
	ds_read_b128 v[222:225], v209 offset:59904
	v_fma_f32 v220, -v186, v82, -v220
	v_fma_f32 v84, v186, s44, v220
	v_fma_f32 v85, v186, s45, v220
	s_mov_b32 s44, 0x41000000
	s_mov_b32 s45, 0x41100000
	v_fma_f32 v86, v186, s44, v220
	v_fma_f32 v87, v186, s45, v220
	s_mov_b32 s44, 0x41200000
	s_mov_b32 s45, 0x41300000
	v_fma_f32 v88, v186, s44, v220
	v_fma_f32 v89, v186, s45, v220
	s_mov_b32 s44, 0x41800000
	s_mov_b32 s45, 0x41880000
	v_fma_f32 v90, v186, s44, v220
	v_fma_f32 v91, v186, s45, v220
	s_mov_b32 s44, 0x41900000
	s_mov_b32 s45, 0x41980000
	v_fma_f32 v92, v186, s44, v220
	v_fma_f32 v93, v186, s45, v220
	s_mov_b32 s44, 0x42680000
	s_mov_b32 s45, 0x426c0000
	v_fma_f32 v112, v186, s44, v220
	v_fma_f32 v113, v186, s45, v220
	s_mov_b32 s44, 0x42400000
	v_fma_f32 v82, 0, v186, v220
	v_add_f32_e32 v83, v186, v220
	v_fma_f32 v94, v186, s50, v220
	v_fma_f32 v95, v186, s51, v220
	v_fma_f32 v96, v186, s28, v220
	v_fma_f32 v97, v186, s29, v220
	s_mov_b32 s45, 0x42440000
	v_fma_f32 v110, v186, s30, v220
	v_fma_f32 v111, v186, s31, v220
	s_waitcnt lgkmcnt(1)
	v_mfma_f32_32x32x16_bf16 v[82:97], v[98:101], v[126:129], v[82:97]
	v_fma_f32 v108, v186, s10, v220
	v_fma_f32 v109, v186, s11, v220
	v_fma_f32 v106, v186, s44, v220
	v_fma_f32 v107, v186, s45, v220
	v_fma_f32 v104, v186, s72, v220
	v_fma_f32 v105, v186, s73, v220
	v_fma_f32 v102, v186, s74, v220
	v_fma_f32 v103, v186, s75, v220
	v_fma_f32 v100, v186, s76, v220
	v_fma_f32 v101, v186, s77, v220
	v_fma_f32 v98, v186, s78, v220
	v_fma_f32 v99, v186, s79, v220
	s_waitcnt lgkmcnt(0)
	s_nop 0
	v_mfma_f32_32x32x16_bf16 v[98:113], v[222:225], v[126:129], v[98:113]
	ds_read_b128 v[232:235], v209 offset:55328
	ds_read_b128 v[126:129], v209 offset:59936
	s_waitcnt lgkmcnt(1)
	v_mfma_f32_32x32x16_bf16 v[82:97], v[232:235], v[122:125], v[82:97]
	s_waitcnt lgkmcnt(0)
	v_mfma_f32_32x32x16_bf16 v[98:113], v[126:129], v[122:125], v[98:113]
	ds_read_b128 v[122:125], v209 offset:55360
	v_add_u32_e32 v126, -1, v219
	v_cmp_gt_u32_e32 vcc, s95, v126
	s_waitcnt lgkmcnt(0)
	v_mfma_f32_32x32x16_bf16 v[82:97], v[122:125], v[118:121], v[82:97]
	ds_read_b128 v[122:125], v209 offset:59968
	s_waitcnt lgkmcnt(0)
	v_mfma_f32_32x32x16_bf16 v[98:113], v[122:125], v[118:121], v[98:113]
	ds_read_b128 v[118:121], v209 offset:55392
	ds_read_b128 v[122:125], v209 offset:60000
	s_waitcnt lgkmcnt(1)
	v_mfma_f32_32x32x16_bf16 v[82:97], v[118:121], v[114:117], v[82:97]
	s_waitcnt lgkmcnt(0)
	v_mfma_f32_32x32x16_bf16 v[98:113], v[122:125], v[114:117], v[98:113]
	s_nop 9
	v_cndmask_b32_e32 v118, v199, v83, vcc
	v_cmp_gt_u32_e32 vcc, s95, v219
	v_subrev_u32_e32 v83, 32, v219
	s_nop 0
	v_cndmask_b32_e32 v119, v199, v82, vcc
	v_subrev_u32_e32 v82, 33, v219
	v_cmp_gt_u32_e32 vcc, s95, v82
	v_add_u32_e32 v82, -3, v219
	s_nop 0
	v_cndmask_b32_e32 v99, v199, v99, vcc
	v_cmp_gt_u32_e32 vcc, s95, v83
	v_add_u32_e32 v83, -2, v219
	s_nop 0
	v_cndmask_b32_e32 v114, v199, v98, vcc
	v_cmp_gt_u32_e32 vcc, s95, v82
	v_subrev_u32_e32 v82, 35, v219
	s_nop 0
	v_cndmask_b32_e32 v115, v199, v85, vcc
	v_cmp_gt_u32_e32 vcc, s95, v83
	v_subrev_u32_e32 v83, 34, v219
	v_subrev_u32_e32 v85, 18, v219
	v_cndmask_b32_e32 v116, v199, v84, vcc
	v_cmp_gt_u32_e32 vcc, s95, v82
	v_add_u32_e32 v82, -9, v219
	v_subrev_u32_e32 v84, 19, v219
	v_cndmask_b32_e32 v98, v199, v101, vcc
	v_cmp_gt_u32_e32 vcc, s95, v83
	v_add_u32_e32 v83, -8, v219
	s_nop 0
	v_cndmask_b32_e32 v100, v199, v100, vcc
	v_cmp_gt_u32_e32 vcc, s95, v82
	v_subrev_u32_e32 v82, 41, v219
	s_nop 0
	v_cndmask_b32_e32 v117, v199, v87, vcc
	v_cmp_gt_u32_e32 vcc, s95, v83
	v_subrev_u32_e32 v83, 40, v219
	s_nop 0
	v_cndmask_b32_e32 v120, v199, v86, vcc
	v_cmp_gt_u32_e32 vcc, s95, v82
	v_add_u32_e32 v82, -11, v219
	s_nop 0
	v_cndmask_b32_e32 v86, v199, v103, vcc
	v_cmp_gt_u32_e32 vcc, s95, v83
	v_add_u32_e32 v83, -10, v219
	s_nop 0
	v_cndmask_b32_e32 v87, v199, v102, vcc
	v_cmp_gt_u32_e32 vcc, s95, v82
	v_subrev_u32_e32 v82, 43, v219
	s_nop 0
	v_cndmask_b32_e32 v121, v199, v89, vcc
	v_cmp_gt_u32_e32 vcc, s95, v83
	v_subrev_u32_e32 v83, 42, v219
	s_nop 0
	v_cndmask_b32_e32 v122, v199, v88, vcc
	v_cmp_gt_u32_e32 vcc, s95, v82
	v_subrev_u32_e32 v82, 17, v219
	s_nop 0
	v_cndmask_b32_e32 v88, v199, v105, vcc
	v_cmp_gt_u32_e32 vcc, s95, v83
	v_add_u32_e32 v83, -16, v219
	s_nop 0
	v_cndmask_b32_e32 v89, v199, v104, vcc
	v_cmp_gt_u32_e32 vcc, s95, v82
	v_subrev_u32_e32 v82, 49, v219
	s_nop 0
	v_cndmask_b32_e32 v101, v199, v91, vcc
	v_cmp_gt_u32_e32 vcc, s95, v83
	v_subrev_u32_e32 v83, 48, v219
	v_subrev_u32_e32 v91, 24, v219
	v_cndmask_b32_e32 v103, v199, v90, vcc
	v_cmp_gt_u32_e32 vcc, s95, v82
	v_subrev_u32_e32 v90, 25, v219
	s_nop 0
	v_cndmask_b32_e32 v82, v199, v107, vcc
	v_cmp_gt_u32_e32 vcc, s95, v83
	s_nop 1
	v_cndmask_b32_e32 v83, v199, v106, vcc
	v_cmp_gt_u32_e32 vcc, s95, v84
	v_subrev_u32_e32 v84, 51, v219
	s_nop 0
	v_cndmask_b32_e32 v102, v199, v93, vcc
	v_cmp_gt_u32_e32 vcc, s95, v85
	v_subrev_u32_e32 v85, 50, v219
	v_subrev_u32_e32 v93, 26, v219
	v_cndmask_b32_e32 v104, v199, v92, vcc
	v_cmp_gt_u32_e32 vcc, s95, v84
	v_subrev_u32_e32 v92, 27, v219
	s_nop 0
	v_cndmask_b32_e32 v84, v199, v109, vcc
	v_cmp_gt_u32_e32 vcc, s95, v85
	s_nop 1
	v_cndmask_b32_e32 v85, v199, v108, vcc
	v_cmp_gt_u32_e32 vcc, s95, v90
	v_subrev_u32_e32 v90, 57, v219
	s_nop 0
	v_cndmask_b32_e32 v95, v199, v95, vcc
	v_cmp_gt_u32_e32 vcc, s95, v91
	v_subrev_u32_e32 v91, 56, v219
	s_nop 0
	v_cndmask_b32_e32 v94, v199, v94, vcc
	v_cmp_gt_u32_e32 vcc, s95, v90
	s_nop 1
	v_cndmask_b32_e32 v90, v199, v111, vcc
	v_cmp_gt_u32_e32 vcc, s95, v91
	s_nop 1
	v_cndmask_b32_e32 v91, v199, v110, vcc
	v_cmp_gt_u32_e32 vcc, s95, v92
	v_subrev_u32_e32 v92, 59, v219
	s_nop 0
	v_cndmask_b32_e32 v97, v199, v97, vcc
	v_cmp_gt_u32_e32 vcc, s95, v93
	v_subrev_u32_e32 v93, 58, v219
	s_nop 0
	v_cndmask_b32_e32 v96, v199, v96, vcc
	v_cmp_gt_u32_e32 vcc, s95, v92
	s_nop 1
	v_cndmask_b32_e32 v92, v199, v113, vcc
	v_cmp_gt_u32_e32 vcc, s95, v93
	s_nop 1
	v_cndmask_b32_e32 v93, v199, v112, vcc
	v_cmp_nge_f32_e32 vcc, s9, v50
	s_cbranch_vccz .LBB0_318
; DI float ex2(float x) { return __builtin_amdgcn_exp2f(x); }
; DI float lg2(float x) { return __builtin_amdgcn_logf(x); }
; template <int MODE, int KS0, int NKS>
; DI void softmax_pv(const bf16x8 (&qf)[4], const u16* Ks, const u16* Vs, float& m, f32x16& ls, f32x16& o0, f32x16& o1,
;                    float sl2, int dl, bool need_mask, bool first, int r, int h, int rs, const int (&lo)[4]) {
;     ...
;   if (__any(first || !(ls[0] <= 1.0e12f))) {
;     float tmax = -INFINITY;
; #pragma unroll
;     for (int i = 0; i < 16; ++i) tmax = fmaxf(tmax, fmaxf(s0[i], s1[i]));
;     tmax = fmaxf(tmax, shx(tmax, r + 32 * h));
;     const float lref = (ls[0] > 1.f) ? lg2(ls[0]) : 0.f;
;     const float delta = first ? tmax : fmaxf(fmaxf(tmax, lref), 0.f);
;     m += delta;
;     const float alpha = ex2(-delta);
; #pragma unroll
;     for (int e = 0; e < 16; ++e) { o0[e] *= alpha; o1[e] *= alpha; ls[e] *= alpha; }
; #pragma unroll
;     for (int i = 0; i < 16; ++i) { s0[i] -= delta; s1[i] -= delta; }
;   }
	v_max_f32_e32 v105, v114, v114
	v_max_f32_e32 v106, v119, v119
	v_max_f32_e32 v105, v106, v105
	v_max_f32_e32 v106, v99, v99
	v_max_f32_e32 v107, v118, v118
	v_max_f32_e32 v106, v107, v106
	s_mov_b32 s19, 0xff800000
	v_max3_f32 v105, v105, s19, v106
	v_max_f32_e32 v106, v100, v100
	v_max_f32_e32 v107, v116, v116
	v_max_f32_e32 v106, v107, v106
	v_max_f32_e32 v107, v98, v98
	v_max_f32_e32 v108, v115, v115
	v_max_f32_e32 v107, v108, v107
	v_max3_f32 v105, v105, v106, v107
	v_max_f32_e32 v106, v87, v87
	v_max_f32_e32 v107, v120, v120
	v_max_f32_e32 v106, v107, v106
	v_max_f32_e32 v107, v86, v86
	v_max_f32_e32 v108, v117, v117
	v_max_f32_e32 v107, v108, v107
	v_max3_f32 v105, v105, v106, v107
	v_max_f32_e32 v106, v89, v89
	v_max_f32_e32 v107, v122, v122
	v_max_f32_e32 v106, v107, v106
	v_max_f32_e32 v107, v88, v88
	v_max_f32_e32 v108, v121, v121
	v_max_f32_e32 v107, v108, v107
	v_max3_f32 v105, v105, v106, v107
	v_max_f32_e32 v106, v83, v83
	v_max_f32_e32 v107, v103, v103
	v_max_f32_e32 v106, v107, v106
	v_max_f32_e32 v107, v82, v82
	v_max_f32_e32 v108, v101, v101
	v_max_f32_e32 v107, v108, v107
	v_max3_f32 v105, v105, v106, v107
	v_max_f32_e32 v106, v85, v85
	v_max_f32_e32 v107, v104, v104
	v_max_f32_e32 v106, v107, v106
	v_max_f32_e32 v107, v84, v84
	v_max_f32_e32 v108, v102, v102
	v_max_f32_e32 v107, v108, v107
	v_max3_f32 v105, v105, v106, v107
	v_max_f32_e32 v106, v91, v91
	v_max_f32_e32 v107, v94, v94
	v_max_f32_e32 v106, v107, v106
	v_max_f32_e32 v107, v90, v90
	v_max_f32_e32 v108, v95, v95
	v_max_f32_e32 v107, v108, v107
	v_max3_f32 v105, v105, v106, v107
	v_max_f32_e32 v106, v93, v93
	v_max_f32_e32 v107, v96, v96
	v_max_f32_e32 v106, v107, v106
	v_max_f32_e32 v107, v92, v92
	v_max_f32_e32 v108, v97, v97
	v_max_f32_e32 v107, v108, v107
	v_max3_f32 v105, v105, v106, v107
	ds_bpermute_b32 v106, v185, v105
	v_log_f32_e32 v107, v50
	v_cmp_lt_f32_e32 vcc, 1.0, v50
	s_waitcnt lgkmcnt(0)
	v_max_f32_e32 v106, v106, v106
	v_max_f32_e32 v105, v105, v106
	v_cndmask_b32_e32 v106, 0, v107, vcc
	v_max3_f32 v105, v105, v106, 0
	v_exp_f32_e64 v106, -v105
	v_sub_f32_e32 v119, v119, v105
	v_sub_f32_e32 v118, v118, v105
	v_sub_f32_e32 v116, v116, v105
	v_mul_f32_e32 v80, v80, v106
	v_mul_f32_e32 v81, v81, v106
	v_mul_f32_e32 v78, v78, v106
	v_mul_f32_e32 v79, v79, v106
	v_mul_f32_e32 v76, v76, v106
	v_mul_f32_e32 v77, v77, v106
	v_mul_f32_e32 v74, v74, v106
	v_mul_f32_e32 v75, v75, v106
	v_mul_f32_e32 v72, v72, v106
	v_mul_f32_e32 v73, v73, v106
	v_mul_f32_e32 v70, v70, v106
	v_mul_f32_e32 v71, v71, v106
	v_mul_f32_e32 v68, v68, v106
	v_mul_f32_e32 v69, v69, v106
	v_mul_f32_e32 v66, v66, v106
	v_mul_f32_e32 v67, v67, v106
	v_mul_f32_e32 v48, v48, v106
	v_mul_f32_e32 v49, v49, v106
	v_mul_f32_e32 v46, v46, v106
	v_mul_f32_e32 v47, v47, v106
	v_mul_f32_e32 v44, v44, v106
	v_mul_f32_e32 v45, v45, v106
	v_mul_f32_e32 v42, v42, v106
	v_mul_f32_e32 v43, v43, v106
	v_mul_f32_e32 v40, v40, v106
	v_mul_f32_e32 v41, v41, v106
	v_mul_f32_e32 v38, v38, v106
	v_mul_f32_e32 v39, v39, v106
	v_mul_f32_e32 v36, v36, v106
	v_mul_f32_e32 v37, v37, v106
	v_mul_f32_e32 v34, v34, v106
	v_mul_f32_e32 v35, v35, v106
	v_mul_f32_e32 v64, v64, v106
	v_mul_f32_e32 v65, v65, v106
	v_mul_f32_e32 v62, v62, v106
	v_mul_f32_e32 v63, v63, v106
	v_mul_f32_e32 v60, v60, v106
	v_mul_f32_e32 v61, v61, v106
	v_mul_f32_e32 v58, v58, v106
	v_mul_f32_e32 v59, v59, v106
	v_mul_f32_e32 v56, v56, v106
	v_mul_f32_e32 v57, v57, v106
	v_mul_f32_e32 v54, v54, v106
	v_mul_f32_e32 v55, v55, v106
	v_mul_f32_e32 v52, v52, v106
	v_mul_f32_e32 v53, v53, v106
	v_mul_f32_e32 v50, v50, v106
	v_mul_f32_e32 v51, v51, v106
	v_sub_f32_e32 v115, v115, v105
	v_sub_f32_e32 v120, v120, v105
	v_sub_f32_e32 v117, v117, v105
	v_sub_f32_e32 v122, v122, v105
	v_sub_f32_e32 v121, v121, v105
	v_sub_f32_e32 v103, v103, v105
	v_sub_f32_e32 v101, v101, v105
	v_sub_f32_e32 v104, v104, v105
	v_sub_f32_e32 v102, v102, v105
	v_sub_f32_e32 v94, v94, v105
	v_sub_f32_e32 v95, v95, v105
	v_sub_f32_e32 v96, v96, v105
	v_sub_f32_e32 v97, v97, v105
	v_sub_f32_e32 v114, v114, v105
	v_sub_f32_e32 v99, v99, v105
	v_sub_f32_e32 v100, v100, v105
	v_sub_f32_e32 v98, v98, v105
	v_sub_f32_e32 v87, v87, v105
	v_sub_f32_e32 v86, v86, v105
	v_sub_f32_e32 v89, v89, v105
	v_sub_f32_e32 v88, v88, v105
	v_sub_f32_e32 v83, v83, v105
	v_sub_f32_e32 v82, v82, v105
	v_sub_f32_e32 v85, v85, v105
	v_sub_f32_e32 v84, v84, v105
	v_sub_f32_e32 v91, v91, v105
	v_sub_f32_e32 v90, v90, v105
	v_sub_f32_e32 v93, v93, v105
	v_sub_f32_e32 v92, v92, v105
; DI float ex2(float x) { return __builtin_amdgcn_exp2f(x); }
; DI f32x16 mfma(bf16x8 a, bf16x8 b, f32x16 c) { return __builtin_amdgcn_mfma_f32_32x32x16_bf16(a, b, c, 0, 0, 0); }
; template <int MODE, int KS0, int NKS>
; DI void softmax_pv(const bf16x8 (&qf)[4], const u16* Ks, const u16* Vs, float& m, f32x16& ls, f32x16& o0, f32x16& o1,
;                    float sl2, int dl, bool need_mask, bool first, int r, int h, int rs, const int (&lo)[4]) {
;     ...
; #pragma unroll
;   for (int i = 0; i < 16; ++i) { s0[i] = ex2(s0[i]); s1[i] = ex2(s1[i]); }
;   const u32x4 one4 = {0x3f803f80u, 0x3f803f80u, 0x3f803f80u, 0x3f803f80u};
;   const bf16x8 ones = __builtin_bit_cast(bf16x8, one4);
; #pragma unroll
;   for (int kk = 0; kk < 4; ++kk) {
;     const int s = kk & 1;
;     unsigned u0, u1, u2, u3;
;     if (kk < 2) {
;       u0 = pk2(s0[8 * s], s0[8 * s + 1]); u1 = pk2(s0[8 * s + 2], s0[8 * s + 3]);
;       u2 = pk2(s0[8 * s + 4], s0[8 * s + 5]); u3 = pk2(s0[8 * s + 6], s0[8 * s + 7]);
;     } else {
;       u0 = pk2(s1[8 * s], s1[8 * s + 1]); u1 = pk2(s1[8 * s + 2], s1[8 * s + 3]);
;       u2 = pk2(s1[8 * s + 4], s1[8 * s + 5]); u3 = pk2(s1[8 * s + 6], s1[8 * s + 7]);
;     }
;     u32x4 uu = {u0, u1, u2, u3};
;     bf16x8 pf = __builtin_bit_cast(bf16x8, uu);
;     bf16x8 v0 = ldsv(Vs + lo[kk]);
;     bf16x8 v1 = ldsv(Vs + 32 * rs + lo[kk]);
;     o0 = mfma(v0, pf, o0);
;     o1 = mfma(v1, pf, o1);
;     ls = mfma(ones, pf, ls);
;   }
; DI void attn_item_B2(const Params& p, int layer, int b, int head0, int qblk, u16* sm, int wv) {
;     ...
;   for (int hh = 0; hh < 2; ++hh) {
;     const int head = head0 + hh;
;     const float sl2 = exp2f(-8.f * (float)(1 + head) / 12.f) * LOG2E;
; #pragma unroll
;     for (int e = 0; e < 16; ++e) { o[hh][0][e] = zf; o[hh][1][e] = zf; ls[hh][e] = onef; }
;     mref[hh] = p.sinks[layer * 8 + head] * LOG2E;
; #pragma unroll
;     for (int c = 0; c < 4; ++c) {
;       if (c >= it0) {
;         const int k0 = q0 - 128 + 64 * c;
;         const bool skip = (k0 > q0w + 31) || (k0 + 63 < q0w - 127);
;         if (!skip) {
;           const int dl = qpos - k0 - 4 * h;
.LBB0_318:
	ds_read_b128 v[106:109], v209 offset:64512
	v_exp_f32_e32 v105, v122
	v_exp_f32_e32 v110, v121
	v_exp_f32_e32 v111, v120
	v_exp_f32_e32 v112, v117
	v_exp_f32_e32 v116, v116
	v_exp_f32_e32 v115, v115
	v_exp_f32_e32 v117, v119
	v_exp_f32_e32 v118, v118
	v_cvt_pk_bf16_f32 v113, v105, v110
	v_cvt_pk_bf16_f32 v112, v111, v112
	v_cvt_pk_bf16_f32 v111, v116, v115
	v_cvt_pk_bf16_f32 v110, v117, v118
	v_lshl_add_u32 v115, v159, 1, v200
	s_mov_b32 s98, s96
	s_waitcnt lgkmcnt(0)
	v_mfma_f32_32x32x16_bf16 v[66:81], v[106:109], v[110:113], v[66:81]
	ds_read_b128 v[106:109], v115
	s_mov_b32 s99, s96
	v_exp_f32_e32 v120, v104
	s_mov_b32 s97, s96
	ds_read_b128 v[116:119], v209 offset:64544
	v_exp_f32_e32 v103, v103
	v_exp_f32_e32 v94, v94
	s_waitcnt lgkmcnt(1)
	v_mfma_f32_32x32x16_bf16 v[34:49], v[106:109], v[110:113], v[34:49]
	v_mov_b64_e32 v[106:107], s[98:99]
	v_mov_b64_e32 v[104:105], s[96:97]
	v_exp_f32_e32 v96, v96
	v_exp_f32_e32 v97, v97
	v_exp_f32_e32 v95, v95
	v_exp_f32_e32 v102, v102
	v_exp_f32_e32 v101, v101
	v_mfma_f32_32x32x16_bf16 v[50:65], v[104:107], v[110:113], v[50:65]
	ds_read_b128 v[108:111], v115 offset:32
	v_cvt_pk_bf16_f32 v97, v96, v97
	v_cvt_pk_bf16_f32 v96, v94, v95
	v_cvt_pk_bf16_f32 v95, v120, v102
	v_cvt_pk_bf16_f32 v94, v103, v101
	v_exp_f32_e32 v87, v87
	v_exp_f32_e32 v89, v89
	s_waitcnt lgkmcnt(1)
	v_mfma_f32_32x32x16_bf16 v[66:81], v[116:119], v[94:97], v[66:81]
	v_exp_f32_e32 v88, v88
	v_exp_f32_e32 v86, v86
	v_exp_f32_e32 v93, v93
	v_exp_f32_e32 v92, v92
	v_cvt_pk_bf16_f32 v89, v89, v88
	v_cvt_pk_bf16_f32 v88, v87, v86
	v_exp_f32_e32 v91, v91
	s_waitcnt lgkmcnt(0)
	v_mfma_f32_32x32x16_bf16 v[34:49], v[108:111], v[94:97], v[34:49]
	v_exp_f32_e32 v108, v114
	v_exp_f32_e32 v109, v100
	ds_read_b128 v[100:103], v209 offset:64576
	v_exp_f32_e32 v90, v90
	v_exp_f32_e32 v82, v82
	v_readlane_b32 s97, v250, 29
	v_mfma_f32_32x32x16_bf16 v[50:65], v[104:107], v[94:97], v[50:65]
	v_exp_f32_e32 v94, v98
	v_exp_f32_e32 v95, v99
	v_cvt_pk_bf16_f32 v87, v109, v94
	v_cvt_pk_bf16_f32 v86, v108, v95
	ds_read_b128 v[94:97], v115 offset:64
	s_waitcnt lgkmcnt(1)
	v_mfma_f32_32x32x16_bf16 v[66:81], v[100:103], v[86:89], v[66:81]
	s_waitcnt lgkmcnt(0)
	v_mfma_f32_32x32x16_bf16 v[34:49], v[94:97], v[86:89], v[34:49]
	v_exp_f32_e32 v94, v85
	v_exp_f32_e32 v95, v84
	v_exp_f32_e32 v96, v83
	v_cvt_pk_bf16_f32 v85, v93, v92
	v_cvt_pk_bf16_f32 v84, v91, v90
	v_cvt_pk_bf16_f32 v83, v94, v95
	v_cvt_pk_bf16_f32 v82, v96, v82
	v_mfma_f32_32x32x16_bf16 v[50:65], v[104:107], v[86:89], v[50:65]
	ds_read_b128 v[232:235], v209 offset:64608
	ds_read_b128 v[86:89], v115 offset:96
	s_waitcnt lgkmcnt(1)
	v_mfma_f32_32x32x16_bf16 v[66:81], v[232:235], v[82:85], v[66:81]
	s_waitcnt lgkmcnt(0)
	v_mfma_f32_32x32x16_bf16 v[34:49], v[86:89], v[82:85], v[34:49]
	v_mfma_f32_32x32x16_bf16 v[50:65], v[104:107], v[82:85], v[50:65]
.LBB0_319:
	s_or_b64 exec, exec, s[2:3]
	s_nop 10
	global_load_dword v51, v1, s[0:1] offset:4
	s_add_i32 s18, s18, 2
	v_cvt_f32_i32_e32 v52, s18
	s_mov_b32 s2, 0x41400000
	v_mov_b64_e32 v[96:97], v[16:17]
	v_mov_b64_e32 v[94:95], v[14:15]
	v_mul_f32_e32 v52, 0xc1000000, v52
	v_div_scale_f32 v53, s[0:1], s2, s2, v52
	v_rcp_f32_e32 v54, v53
	v_div_scale_f32 v55, vcc, v52, s2, v52
	v_mov_b64_e32 v[92:93], v[12:13]
	v_fma_f32 v56, -v53, v54, 1.0
	v_fmac_f32_e32 v54, v56, v54
	v_mul_f32_e32 v56, v55, v54
	v_fma_f32 v57, -v53, v56, v55
	v_fmac_f32_e32 v56, v57, v54
	v_fma_f32 v53, -v53, v56, v55
	v_div_fmas_f32 v53, v53, v54, v56
	v_div_fixup_f32 v52, v53, s2, v52
	v_cmp_gt_f32_e32 vcc, s94, v52
	s_and_b64 s[0:1], vcc, exec
	s_cselect_b32 s0, 0xffffffc0, 0
	v_cndmask_b32_e32 v53, 0, v187, vcc
	v_add_f32_e32 v52, v52, v53
	v_exp_f32_e32 v52, v52
	v_mov_b64_e32 v[90:91], v[10:11]
	v_mov_b64_e32 v[88:89], v[8:9]
	v_mov_b64_e32 v[86:87], v[6:7]
	v_ldexp_f32 v52, v52, s0
	v_mul_f32_e32 v56, 0x3fb8aa3b, v52
	v_mov_b64_e32 v[84:85], v[4:5]
	v_mov_b64_e32 v[82:83], v[2:3]
	s_waitcnt vmcnt(0)
	v_mul_f32_e32 v51, 0x3fb8aa3b, v51
	s_and_saveexec_b64 s[0:1], s[36:37]
	s_cbranch_execz .LBB0_329
	v_cmp_le_i32_e32 vcc, v212, v210
	v_cmp_ge_i32_e64 s[2:3], v216, v211
	v_mov_b64_e32 v[112:113], v[16:17]
	s_and_b64 s[18:19], vcc, s[2:3]
	v_mov_b64_e32 v[110:111], v[14:15]
	v_mov_b64_e32 v[108:109], v[12:13]
	v_mov_b64_e32 v[106:107], v[10:11]
	v_mov_b64_e32 v[104:105], v[8:9]
	v_mov_b64_e32 v[102:103], v[6:7]
	v_mov_b64_e32 v[100:101], v[4:5]
	v_mov_b64_e32 v[98:99], v[2:3]
	s_and_saveexec_b64 s[2:3], s[18:19]
	s_cbranch_execz .LBB0_324
; DI f32x16 mfma(bf16x8 a, bf16x8 b, f32x16 c) { return __builtin_amdgcn_mfma_f32_32x32x16_bf16(a, b, c, 0, 0, 0); }
; template <int MODE, int KS0, int NKS>
; DI void qk_scores(f32x16& s0, f32x16& s1, const u16* Ks, const bf16x8 (&qf)[4], float sl2, int dl, float mref,
;                   bool need_mask, int r, int h, int rs, const int (&lo)[4]) {
;     ...
;   const float nb = -sl2 * (float)dl - mref;
; #pragma unroll
;   for (int i = 0; i < 16; ++i) {
;     const int ci = (i & 3) + 8 * (i >> 2);
;     s0[i] = fmaf(sl2, (float)ci, nb);
;     s1[i] = fmaf(sl2, (float)(ci + 32), nb);
;   }
; #pragma unroll
;   for (int ks = 0; ks < NKS; ++ks) {
;     bf16x8 k0 = ldsv(Ks + lo[KS0 + ks]);
;     bf16x8 k1 = ldsv(Ks + 32 * rs + lo[KS0 + ks]);
;     s0 = mfma(k0, qf[KS0 + ks], s0);
;     s1 = mfma(k1, qf[KS0 + ks], s1);
;   }
;   if (need_mask) {
; #pragma unroll
;     for (int i = 0; i < 16; ++i) {
;       const int ci = (i & 3) + 8 * (i >> 2);
;       bool v0 = (MODE == 0) ? (ci <= dl) : (ci <= dl && ci > dl - 128);
;       bool v1 = (MODE == 0) ? (ci + 32 <= dl) : (ci + 32 <= dl && ci + 32 > dl - 128);
;       s0[i] = v0 ? s0[i] : -INFINITY;
;       s1[i] = v1 ? s1[i] : -INFINITY;
;     }
;   }
	v_add3_u32 v3, v214, v213, v208
	s_mov_b32 s18, 2.0
	v_cvt_f32_i32_e32 v8, v3
	s_mov_b32 s19, 0x40400000
	ds_read_b128 v[4:7], v209
	v_fma_f32 v12, -v56, v8, -v51
	v_fma_f32 v84, v56, s18, v12
	v_fma_f32 v85, v56, s19, v12
	s_mov_b32 s18, 0x41000000
	s_mov_b32 s19, 0x41100000
	v_fma_f32 v86, v56, s18, v12
	v_fma_f32 v87, v56, s19, v12
	s_mov_b32 s18, 0x41200000
	s_mov_b32 s19, 0x41300000
	v_fma_f32 v88, v56, s18, v12
	v_fma_f32 v89, v56, s19, v12
	s_mov_b32 s18, 0x41800000
	s_mov_b32 s19, 0x41880000
	v_fma_f32 v90, v56, s18, v12
	v_fma_f32 v91, v56, s19, v12
	s_mov_b32 s18, 0x41900000
	s_mov_b32 s19, 0x41980000
	v_fma_f32 v82, 0, v56, v12
	v_add_f32_e32 v83, v56, v12
	v_fma_f32 v92, v56, s18, v12
	v_fma_f32 v93, v56, s19, v12
	v_fma_f32 v94, v56, s50, v12
	v_fma_f32 v95, v56, s51, v12
	v_fma_f32 v96, v56, s28, v12
	v_fma_f32 v97, v56, s29, v12
	ds_read_b128 v[8:11], v209 offset:4608
	s_mov_b32 s18, 0x42680000
	s_waitcnt lgkmcnt(1)
	v_mfma_f32_32x32x16_bf16 v[82:97], v[4:7], v[142:145], v[82:97]
	ds_read_b128 v[4:7], v209 offset:32
	s_mov_b32 s19, 0x426c0000
	v_fma_f32 v112, v56, s18, v12
	v_fma_f32 v113, v56, s19, v12
	s_mov_b32 s18, 0x42400000
	s_mov_b32 s19, 0x42440000
	v_fma_f32 v110, v56, s30, v12
	v_fma_f32 v111, v56, s31, v12
	v_fma_f32 v108, v56, s10, v12
	v_fma_f32 v109, v56, s11, v12
	v_fma_f32 v106, v56, s18, v12
	v_fma_f32 v107, v56, s19, v12
	v_fma_f32 v104, v56, s72, v12
	v_fma_f32 v105, v56, s73, v12
	v_fma_f32 v102, v56, s74, v12
	v_fma_f32 v103, v56, s75, v12
	v_fma_f32 v100, v56, s76, v12
	v_fma_f32 v101, v56, s77, v12
	v_fma_f32 v98, v56, s78, v12
	v_fma_f32 v99, v56, s79, v12
	s_waitcnt lgkmcnt(0)
	v_mfma_f32_32x32x16_bf16 v[82:97], v[4:7], v[138:141], v[82:97]
	ds_read_b128 v[4:7], v209 offset:4640
	v_add_u32_e32 v12, -1, v3
	v_cmp_gt_u32_e32 vcc, s95, v12
	v_mfma_f32_32x32x16_bf16 v[98:113], v[8:11], v[142:145], v[98:113]
	s_waitcnt lgkmcnt(0)
	v_mfma_f32_32x32x16_bf16 v[98:113], v[4:7], v[138:141], v[98:113]
	ds_read_b128 v[232:235], v209 offset:64
	ds_read_b128 v[4:7], v209 offset:4672
	s_waitcnt lgkmcnt(1)
	v_mfma_f32_32x32x16_bf16 v[82:97], v[232:235], v[134:137], v[82:97]
	s_waitcnt lgkmcnt(0)
	v_mfma_f32_32x32x16_bf16 v[98:113], v[4:7], v[134:137], v[98:113]
	ds_read_b128 v[4:7], v209 offset:96
	ds_read_b128 v[8:11], v209 offset:4704
	s_waitcnt lgkmcnt(1)
	v_mfma_f32_32x32x16_bf16 v[82:97], v[4:7], v[130:133], v[82:97]
	v_subrev_u32_e32 v4, 33, v3
	v_subrev_u32_e32 v5, 32, v3
	s_waitcnt lgkmcnt(0)
	v_mfma_f32_32x32x16_bf16 v[98:113], v[8:11], v[130:133], v[98:113]
	s_nop 7
	v_cndmask_b32_e32 v29, v199, v83, vcc
	v_cmp_gt_u32_e32 vcc, s95, v3
	s_nop 1
	v_cndmask_b32_e32 v30, v199, v82, vcc
	v_cmp_gt_u32_e32 vcc, s95, v4
	v_add_u32_e32 v4, -3, v3
	s_nop 0
	v_cndmask_b32_e32 v59, v199, v99, vcc
	v_cmp_gt_u32_e32 vcc, s95, v5
	v_add_u32_e32 v5, -2, v3
	s_nop 0
	v_cndmask_b32_e32 v64, v199, v98, vcc
	v_cmp_gt_u32_e32 vcc, s95, v4
	v_subrev_u32_e32 v4, 35, v3
	s_nop 0
	v_cndmask_b32_e32 v31, v199, v85, vcc
	v_cmp_gt_u32_e32 vcc, s95, v5
	v_subrev_u32_e32 v5, 34, v3
	s_nop 0
	v_cndmask_b32_e32 v32, v199, v84, vcc
	v_cmp_gt_u32_e32 vcc, s95, v4
	v_add_u32_e32 v4, -9, v3
	s_nop 0
	v_cndmask_b32_e32 v62, v199, v101, vcc
	v_cmp_gt_u32_e32 vcc, s95, v5
	v_add_u32_e32 v5, -8, v3
	s_nop 0
	v_cndmask_b32_e32 v65, v199, v100, vcc
	v_cmp_gt_u32_e32 vcc, s95, v4
	v_subrev_u32_e32 v4, 41, v3
	s_nop 0
	v_cndmask_b32_e32 v33, v199, v87, vcc
	v_cmp_gt_u32_e32 vcc, s95, v5
	v_subrev_u32_e32 v5, 40, v3
	s_nop 0
	v_cndmask_b32_e32 v53, v199, v86, vcc
	v_cmp_gt_u32_e32 vcc, s95, v4
	v_add_u32_e32 v4, -11, v3
	s_nop 0
	v_cndmask_b32_e32 v63, v199, v103, vcc
	v_cmp_gt_u32_e32 vcc, s95, v5
	v_add_u32_e32 v5, -10, v3
	s_nop 0
	v_cndmask_b32_e32 v98, v199, v102, vcc
	v_cmp_gt_u32_e32 vcc, s95, v4
	v_subrev_u32_e32 v4, 43, v3
	s_nop 0
	v_cndmask_b32_e32 v55, v199, v89, vcc
	v_cmp_gt_u32_e32 vcc, s95, v5
	v_subrev_u32_e32 v5, 42, v3
	s_nop 0
	v_cndmask_b32_e32 v82, v199, v88, vcc
	v_cmp_gt_u32_e32 vcc, s95, v4
	v_subrev_u32_e32 v4, 17, v3
	s_nop 0
	v_cndmask_b32_e32 v99, v199, v105, vcc
	v_cmp_gt_u32_e32 vcc, s95, v5
	v_add_u32_e32 v5, -16, v3
	s_nop 0
	v_cndmask_b32_e32 v100, v199, v104, vcc
	v_cmp_gt_u32_e32 vcc, s95, v4
	v_subrev_u32_e32 v4, 49, v3
	s_nop 0
	v_cndmask_b32_e32 v105, v199, v91, vcc
	v_cmp_gt_u32_e32 vcc, s95, v5
	v_subrev_u32_e32 v5, 48, v3
	s_nop 0
	v_cndmask_b32_e32 v52, v199, v90, vcc
	v_cmp_gt_u32_e32 vcc, s95, v4
	v_subrev_u32_e32 v4, 19, v3
	s_nop 0
	v_cndmask_b32_e32 v57, v199, v107, vcc
	v_cmp_gt_u32_e32 vcc, s95, v5
	v_subrev_u32_e32 v5, 18, v3
	s_nop 0
	v_cndmask_b32_e32 v58, v199, v106, vcc
	v_cmp_gt_u32_e32 vcc, s95, v4
	v_subrev_u32_e32 v4, 51, v3
	s_nop 0
	v_cndmask_b32_e32 v106, v199, v93, vcc
	v_cmp_gt_u32_e32 vcc, s95, v5
	v_subrev_u32_e32 v5, 50, v3
	s_nop 0
	v_cndmask_b32_e32 v54, v199, v92, vcc
	v_cmp_gt_u32_e32 vcc, s95, v4
	v_subrev_u32_e32 v4, 25, v3
	s_nop 0
	v_cndmask_b32_e32 v60, v199, v109, vcc
	v_cmp_gt_u32_e32 vcc, s95, v5
	v_subrev_u32_e32 v5, 24, v3
	s_nop 0
	v_cndmask_b32_e32 v61, v199, v108, vcc
	v_cmp_gt_u32_e32 vcc, s95, v4
	v_subrev_u32_e32 v4, 57, v3
	s_nop 0
	v_cndmask_b32_e32 v107, v199, v95, vcc
	v_cmp_gt_u32_e32 vcc, s95, v5
	v_subrev_u32_e32 v5, 56, v3
	s_nop 0
	v_cndmask_b32_e32 v108, v199, v94, vcc
	v_cmp_gt_u32_e32 vcc, s95, v4
	v_subrev_u32_e32 v4, 27, v3
	s_nop 0
	v_cndmask_b32_e32 v101, v199, v111, vcc
	v_cmp_gt_u32_e32 vcc, s95, v5
	v_subrev_u32_e32 v5, 26, v3
	s_nop 0
	v_cndmask_b32_e32 v102, v199, v110, vcc
	v_cmp_gt_u32_e32 vcc, s95, v4
	v_subrev_u32_e32 v4, 59, v3
	v_subrev_u32_e32 v3, 58, v3
	v_cndmask_b32_e32 v109, v199, v97, vcc
	v_cmp_gt_u32_e32 vcc, s95, v5
	s_nop 1
	v_cndmask_b32_e32 v110, v199, v96, vcc
	v_cmp_gt_u32_e32 vcc, s95, v4
	s_nop 1
	v_cndmask_b32_e32 v103, v199, v113, vcc
	v_cmp_gt_u32_e32 vcc, s95, v3
	s_nop 1
	v_cndmask_b32_e32 v104, v199, v112, vcc
	v_cmp_nge_f32_e32 vcc, s9, v18
	s_cbranch_vccz .LBB0_323
; DI float ex2(float x) { return __builtin_amdgcn_exp2f(x); }
; DI float lg2(float x) { return __builtin_amdgcn_logf(x); }
; template <int MODE, int KS0, int NKS>
; DI void softmax_pv(const bf16x8 (&qf)[4], const u16* Ks, const u16* Vs, float& m, f32x16& ls, f32x16& o0, f32x16& o1,
;                    float sl2, int dl, bool need_mask, bool first, int r, int h, int rs, const int (&lo)[4]) {
;     ...
;   if (__any(first || !(ls[0] <= 1.0e12f))) {
;     float tmax = -INFINITY;
; #pragma unroll
;     for (int i = 0; i < 16; ++i) tmax = fmaxf(tmax, fmaxf(s0[i], s1[i]));
;     tmax = fmaxf(tmax, shx(tmax, r + 32 * h));
;     const float lref = (ls[0] > 1.f) ? lg2(ls[0]) : 0.f;
;     const float delta = first ? tmax : fmaxf(fmaxf(tmax, lref), 0.f);
;     m += delta;
;     const float alpha = ex2(-delta);
; #pragma unroll
;     for (int e = 0; e < 16; ++e) { o0[e] *= alpha; o1[e] *= alpha; ls[e] *= alpha; }
; #pragma unroll
;     for (int i = 0; i < 16; ++i) { s0[i] -= delta; s1[i] -= delta; }
;   }
	v_max_f32_e32 v3, v64, v64
	v_max_f32_e32 v4, v30, v30
	v_max_f32_e32 v3, v4, v3
	v_max_f32_e32 v4, v59, v59
	v_max_f32_e32 v5, v29, v29
	v_max_f32_e32 v4, v5, v4
	s_mov_b32 s18, 0xff800000
	v_max3_f32 v3, v3, s18, v4
	v_max_f32_e32 v4, v65, v65
	v_max_f32_e32 v5, v32, v32
	v_max_f32_e32 v4, v5, v4
	v_max_f32_e32 v5, v62, v62
	v_max_f32_e32 v6, v31, v31
	v_max_f32_e32 v5, v6, v5
	v_max3_f32 v3, v3, v4, v5
	v_max_f32_e32 v4, v98, v98
	v_max_f32_e32 v5, v53, v53
	v_max_f32_e32 v4, v5, v4
	v_max_f32_e32 v5, v63, v63
	v_max_f32_e32 v6, v33, v33
	v_max_f32_e32 v5, v6, v5
	v_max3_f32 v3, v3, v4, v5
	v_max_f32_e32 v4, v100, v100
	v_max_f32_e32 v5, v82, v82
	v_max_f32_e32 v4, v5, v4
	v_max_f32_e32 v5, v99, v99
	v_max_f32_e32 v6, v55, v55
	v_max_f32_e32 v5, v6, v5
	v_max3_f32 v3, v3, v4, v5
	v_max_f32_e32 v4, v58, v58
	v_max_f32_e32 v5, v52, v52
	v_max_f32_e32 v4, v5, v4
	v_max_f32_e32 v5, v57, v57
	v_max_f32_e32 v6, v105, v105
	v_max_f32_e32 v5, v6, v5
	v_max3_f32 v3, v3, v4, v5
	v_max_f32_e32 v4, v61, v61
	v_max_f32_e32 v5, v54, v54
	v_max_f32_e32 v4, v5, v4
	v_max_f32_e32 v5, v60, v60
	v_max_f32_e32 v6, v106, v106
	v_max_f32_e32 v5, v6, v5
	v_max3_f32 v3, v3, v4, v5
	v_max_f32_e32 v4, v102, v102
	v_max_f32_e32 v5, v108, v108
	v_max_f32_e32 v4, v5, v4
	v_max_f32_e32 v5, v101, v101
	v_max_f32_e32 v6, v107, v107
	v_max_f32_e32 v5, v6, v5
	v_max3_f32 v3, v3, v4, v5
	v_max_f32_e32 v4, v104, v104
	v_max_f32_e32 v5, v110, v110
	v_max_f32_e32 v4, v5, v4
	v_max_f32_e32 v5, v103, v103
	v_max_f32_e32 v6, v109, v109
	v_max_f32_e32 v5, v6, v5
	v_max3_f32 v3, v3, v4, v5
	ds_bpermute_b32 v4, v185, v3
	v_log_f32_e32 v5, v18
	v_cmp_lt_f32_e32 vcc, 1.0, v18
	s_waitcnt lgkmcnt(0)
	v_max_f32_e32 v4, v4, v4
	v_max_f32_e32 v3, v3, v4
	v_cndmask_b32_e32 v4, 0, v5, vcc
	v_max3_f32 v3, v3, v4, 0
	v_exp_f32_e64 v4, -v3
	v_add_f32_e32 v51, v51, v3
	v_sub_f32_e32 v30, v30, v3
	v_sub_f32_e32 v29, v29, v3
	v_mul_f32_e32 v2, v2, v4
	v_mul_f32_e32 v18, v18, v4
	v_sub_f32_e32 v32, v32, v3
	v_sub_f32_e32 v31, v31, v3
	v_sub_f32_e32 v53, v53, v3
	v_sub_f32_e32 v33, v33, v3
	v_sub_f32_e32 v82, v82, v3
	v_sub_f32_e32 v55, v55, v3
	v_sub_f32_e32 v52, v52, v3
	v_sub_f32_e32 v105, v105, v3
	v_sub_f32_e32 v54, v54, v3
	v_sub_f32_e32 v106, v106, v3
	v_sub_f32_e32 v108, v108, v3
	v_sub_f32_e32 v107, v107, v3
	v_sub_f32_e32 v110, v110, v3
	v_sub_f32_e32 v109, v109, v3
	v_sub_f32_e32 v64, v64, v3
	v_sub_f32_e32 v59, v59, v3
	v_sub_f32_e32 v65, v65, v3
	v_sub_f32_e32 v62, v62, v3
	v_sub_f32_e32 v98, v98, v3
	v_sub_f32_e32 v63, v63, v3
	v_sub_f32_e32 v100, v100, v3
	v_sub_f32_e32 v99, v99, v3
	v_sub_f32_e32 v58, v58, v3
	v_sub_f32_e32 v57, v57, v3
	v_sub_f32_e32 v61, v61, v3
	v_sub_f32_e32 v60, v60, v3
	v_sub_f32_e32 v102, v102, v3
	v_sub_f32_e32 v101, v101, v3
	v_sub_f32_e32 v104, v104, v3
	v_sub_f32_e32 v103, v103, v3

; DI f32x16 mfma(bf16x8 a, bf16x8 b, f32x16 c) { return __builtin_amdgcn_mfma_f32_32x32x16_bf16(a, b, c, 0, 0, 0); }
; template <int MODE, int KS0, int NKS>
; DI void qk_scores(f32x16& s0, f32x16& s1, const u16* Ks, const bf16x8 (&qf)[4], float sl2, int dl, float mref,
;                   bool need_mask, int r, int h, int rs, const int (&lo)[4]) {
;     ...
;   const float nb = -sl2 * (float)dl - mref;
; #pragma unroll
;   for (int i = 0; i < 16; ++i) {
;     const int ci = (i & 3) + 8 * (i >> 2);
;     s0[i] = fmaf(sl2, (float)ci, nb);
;     s1[i] = fmaf(sl2, (float)(ci + 32), nb);
;   }
; #pragma unroll
;   for (int ks = 0; ks < NKS; ++ks) {
;     bf16x8 k0 = ldsv(Ks + lo[KS0 + ks]);
;     bf16x8 k1 = ldsv(Ks + 32 * rs + lo[KS0 + ks]);
;     s0 = mfma(k0, qf[KS0 + ks], s0);
;     s1 = mfma(k1, qf[KS0 + ks], s1);
;   }
;   if (need_mask) {
; #pragma unroll
;     for (int i = 0; i < 16; ++i) {
;       const int ci = (i & 3) + 8 * (i >> 2);
;       bool v0 = (MODE == 0) ? (ci <= dl) : (ci <= dl && ci > dl - 128);
;       bool v1 = (MODE == 0) ? (ci + 32 <= dl) : (ci + 32 <= dl && ci + 32 > dl - 128);
;       s0[i] = v0 ? s0[i] : -INFINITY;
;       s1[i] = v1 ? s1[i] : -INFINITY;
;     }
;   }
.LBB0_326:
	s_mov_b32 s2, 2.0
	v_cvt_f32_i32_e32 v57, v215
	s_mov_b32 s3, 0x40400000
	ds_read_b128 v[52:55], v209 offset:36864
	ds_read_b128 v[58:61], v209 offset:41472
	v_fma_f32 v62, -v56, v57, -v51
	v_fma_f32 v100, v56, s2, v62
	v_fma_f32 v101, v56, s3, v62
	s_mov_b32 s2, 0x41000000
	s_mov_b32 s3, 0x41100000
	v_fma_f32 v102, v56, s2, v62
	v_fma_f32 v103, v56, s3, v62
	s_mov_b32 s2, 0x41200000
	s_mov_b32 s3, 0x41300000
	v_fma_f32 v104, v56, s2, v62
	v_fma_f32 v105, v56, s3, v62
	s_mov_b32 s2, 0x41800000
	s_mov_b32 s3, 0x41880000
	v_fma_f32 v106, v56, s2, v62
	v_fma_f32 v107, v56, s3, v62
	s_mov_b32 s2, 0x41900000
	s_mov_b32 s3, 0x41980000
	v_fma_f32 v98, 0, v56, v62
	v_add_f32_e32 v99, v56, v62
	v_fma_f32 v108, v56, s2, v62
	v_fma_f32 v109, v56, s3, v62
	v_fma_f32 v110, v56, s50, v62
	v_fma_f32 v111, v56, s51, v62
	v_fma_f32 v112, v56, s28, v62
	v_fma_f32 v113, v56, s29, v62
	s_mov_b32 s2, 0x42680000
	s_mov_b32 s3, 0x426c0000
	s_waitcnt lgkmcnt(1)
	v_mfma_f32_32x32x16_bf16 v[98:113], v[52:55], v[142:145], v[98:113]
	ds_read_b128 v[52:55], v209 offset:36896
	v_fma_f32 v128, v56, s2, v62
	v_fma_f32 v129, v56, s3, v62
	s_mov_b32 s2, 0x42400000
	s_mov_b32 s3, 0x42440000
	v_fma_f32 v126, v56, s30, v62
	v_fma_f32 v127, v56, s31, v62
	v_fma_f32 v124, v56, s10, v62
	v_fma_f32 v125, v56, s11, v62
	v_fma_f32 v122, v56, s2, v62
	v_fma_f32 v123, v56, s3, v62
	v_fma_f32 v120, v56, s72, v62
	v_fma_f32 v121, v56, s73, v62
	v_fma_f32 v118, v56, s74, v62
	v_fma_f32 v119, v56, s75, v62
	v_fma_f32 v116, v56, s76, v62
	v_fma_f32 v117, v56, s77, v62
	v_fma_f32 v114, v56, s78, v62
	v_fma_f32 v115, v56, s79, v62
	s_waitcnt lgkmcnt(0)
	v_mfma_f32_32x32x16_bf16 v[98:113], v[52:55], v[138:141], v[98:113]
	ds_read_b128 v[52:55], v209 offset:41504
	v_add_u32_e32 v57, -1, v215
	v_cmp_gt_u32_e32 vcc, s95, v57
	v_subrev_u32_e32 v57, 35, v215
	v_mfma_f32_32x32x16_bf16 v[114:129], v[58:61], v[142:145], v[114:129]
	s_waitcnt lgkmcnt(0)
	v_mfma_f32_32x32x16_bf16 v[114:129], v[52:55], v[138:141], v[114:129]
	ds_read_b128 v[232:235], v209 offset:36928
	ds_read_b128 v[52:55], v209 offset:41536
	s_waitcnt lgkmcnt(1)
	v_mfma_f32_32x32x16_bf16 v[98:113], v[232:235], v[134:137], v[98:113]
	s_waitcnt lgkmcnt(0)
	v_mfma_f32_32x32x16_bf16 v[114:129], v[52:55], v[134:137], v[114:129]
	ds_read_b128 v[52:55], v209 offset:36960
	ds_read_b128 v[58:61], v209 offset:41568
	s_waitcnt lgkmcnt(1)
	v_mfma_f32_32x32x16_bf16 v[98:113], v[52:55], v[130:133], v[98:113]
	v_subrev_u32_e32 v54, 33, v215
	v_subrev_u32_e32 v55, 32, v215
	s_waitcnt lgkmcnt(0)
	v_mfma_f32_32x32x16_bf16 v[114:129], v[58:61], v[130:133], v[114:129]
	s_nop 7
	v_cndmask_b32_e32 v52, v199, v99, vcc
	v_cmp_gt_u32_e32 vcc, s95, v215
	v_subrev_u32_e32 v58, 34, v215
	v_subrev_u32_e32 v60, 19, v215
	v_cndmask_b32_e32 v53, v199, v98, vcc
	v_cmp_gt_u32_e32 vcc, s95, v54
	v_add_u32_e32 v54, -3, v215
	v_subrev_u32_e32 v61, 18, v215
	v_cndmask_b32_e32 v59, v199, v115, vcc
	v_cmp_gt_u32_e32 vcc, s95, v55
	v_add_u32_e32 v55, -2, v215
	s_nop 0
	v_cndmask_b32_e32 v64, v199, v114, vcc
	v_cmp_gt_u32_e32 vcc, s95, v54
	s_nop 1
	v_cndmask_b32_e32 v54, v199, v101, vcc
	v_cmp_gt_u32_e32 vcc, s95, v55
	v_subrev_u32_e32 v101, 25, v215
	s_nop 0
	v_cndmask_b32_e32 v55, v199, v100, vcc
	v_cmp_gt_u32_e32 vcc, s95, v57
	v_add_u32_e32 v57, -9, v215
	s_nop 0
	v_cndmask_b32_e32 v62, v199, v117, vcc
	v_cmp_gt_u32_e32 vcc, s95, v58
	v_add_u32_e32 v58, -8, v215
	s_nop 0
	v_cndmask_b32_e32 v65, v199, v116, vcc
	v_cmp_gt_u32_e32 vcc, s95, v57
	v_subrev_u32_e32 v57, 41, v215
	s_nop 0
	v_cndmask_b32_e32 v115, v199, v103, vcc
	v_cmp_gt_u32_e32 vcc, s95, v58
	v_subrev_u32_e32 v58, 40, v215
	v_subrev_u32_e32 v103, 27, v215
	v_cndmask_b32_e32 v116, v199, v102, vcc
	v_cmp_gt_u32_e32 vcc, s95, v57
	v_add_u32_e32 v57, -11, v215
	v_subrev_u32_e32 v102, 24, v215
	v_cndmask_b32_e32 v63, v199, v119, vcc
	v_cmp_gt_u32_e32 vcc, s95, v58
	v_add_u32_e32 v58, -10, v215
	s_nop 0
	v_cndmask_b32_e32 v98, v199, v118, vcc
	v_cmp_gt_u32_e32 vcc, s95, v57
	v_subrev_u32_e32 v57, 43, v215
	s_nop 0
	v_cndmask_b32_e32 v117, v199, v105, vcc
	v_cmp_gt_u32_e32 vcc, s95, v58
	v_subrev_u32_e32 v58, 42, v215
	s_nop 0
	v_cndmask_b32_e32 v118, v199, v104, vcc
	v_cmp_gt_u32_e32 vcc, s95, v57
	v_subrev_u32_e32 v57, 17, v215
	v_subrev_u32_e32 v104, 26, v215
	v_cndmask_b32_e32 v99, v199, v121, vcc
	v_cmp_gt_u32_e32 vcc, s95, v58
	v_add_u32_e32 v58, -16, v215
	s_nop 0
	v_cndmask_b32_e32 v100, v199, v120, vcc
	v_cmp_gt_u32_e32 vcc, s95, v57
	v_subrev_u32_e32 v57, 49, v215
	s_nop 0
	v_cndmask_b32_e32 v105, v199, v107, vcc
	v_cmp_gt_u32_e32 vcc, s95, v58
	v_subrev_u32_e32 v58, 48, v215
	s_nop 0
	v_cndmask_b32_e32 v114, v199, v106, vcc
	v_cmp_gt_u32_e32 vcc, s95, v57
	s_nop 1
	v_cndmask_b32_e32 v57, v199, v123, vcc
	v_cmp_gt_u32_e32 vcc, s95, v58
	s_nop 1
	v_cndmask_b32_e32 v58, v199, v122, vcc
	v_cmp_gt_u32_e32 vcc, s95, v60
	v_subrev_u32_e32 v60, 51, v215
	s_nop 0
	v_cndmask_b32_e32 v106, v199, v109, vcc
	v_cmp_gt_u32_e32 vcc, s95, v61
	v_subrev_u32_e32 v61, 50, v215
	s_nop 0
	v_cndmask_b32_e32 v108, v199, v108, vcc
	v_cmp_gt_u32_e32 vcc, s95, v60
	s_nop 1
	v_cndmask_b32_e32 v60, v199, v125, vcc
	v_cmp_gt_u32_e32 vcc, s95, v61
	s_nop 1
	v_cndmask_b32_e32 v61, v199, v124, vcc
	v_cmp_gt_u32_e32 vcc, s95, v101
	v_subrev_u32_e32 v101, 57, v215
	s_nop 0
	v_cndmask_b32_e32 v107, v199, v111, vcc
	v_cmp_gt_u32_e32 vcc, s95, v102
	v_subrev_u32_e32 v102, 56, v215
	s_nop 0
	v_cndmask_b32_e32 v109, v199, v110, vcc
	v_cmp_gt_u32_e32 vcc, s95, v101
	s_nop 1
	v_cndmask_b32_e32 v101, v199, v127, vcc
	v_cmp_gt_u32_e32 vcc, s95, v102
	s_nop 1
	v_cndmask_b32_e32 v102, v199, v126, vcc
	v_cmp_gt_u32_e32 vcc, s95, v103
	v_subrev_u32_e32 v103, 59, v215
	s_nop 0
	v_cndmask_b32_e32 v110, v199, v113, vcc
	v_cmp_gt_u32_e32 vcc, s95, v104
	v_subrev_u32_e32 v104, 58, v215
	s_nop 0
	v_cndmask_b32_e32 v111, v199, v112, vcc
	v_cmp_gt_u32_e32 vcc, s95, v103
	s_nop 1
	v_cndmask_b32_e32 v103, v199, v129, vcc
	v_cmp_gt_u32_e32 vcc, s95, v104
	s_nop 1
	v_cndmask_b32_e32 v104, v199, v128, vcc
	v_cmp_nge_f32_e32 vcc, s9, v18
	s_cbranch_vccz .LBB0_328
; DI float ex2(float x) { return __builtin_amdgcn_exp2f(x); }
; DI float lg2(float x) { return __builtin_amdgcn_logf(x); }
; template <int MODE, int KS0, int NKS>
; DI void softmax_pv(const bf16x8 (&qf)[4], const u16* Ks, const u16* Vs, float& m, f32x16& ls, f32x16& o0, f32x16& o1,
;                    float sl2, int dl, bool need_mask, bool first, int r, int h, int rs, const int (&lo)[4]) {
;     ...
;   if (__any(first || !(ls[0] <= 1.0e12f))) {
;     float tmax = -INFINITY;
; #pragma unroll
;     for (int i = 0; i < 16; ++i) tmax = fmaxf(tmax, fmaxf(s0[i], s1[i]));
;     tmax = fmaxf(tmax, shx(tmax, r + 32 * h));
;     const float lref = (ls[0] > 1.f) ? lg2(ls[0]) : 0.f;
;     const float delta = first ? tmax : fmaxf(fmaxf(tmax, lref), 0.f);
;     m += delta;
;     const float alpha = ex2(-delta);
; #pragma unroll
;     for (int e = 0; e < 16; ++e) { o0[e] *= alpha; o1[e] *= alpha; ls[e] *= alpha; }
; #pragma unroll
;     for (int i = 0; i < 16; ++i) { s0[i] -= delta; s1[i] -= delta; }
;   }
	v_max_f32_e32 v112, v64, v64
	v_max_f32_e32 v113, v53, v53
	v_max_f32_e32 v112, v113, v112
	v_max_f32_e32 v113, v59, v59
	v_max_f32_e32 v119, v52, v52
	v_max_f32_e32 v113, v119, v113
	s_mov_b32 s2, 0xff800000
	v_max3_f32 v112, v112, s2, v113
	v_max_f32_e32 v113, v65, v65
	v_max_f32_e32 v119, v55, v55
	v_max_f32_e32 v113, v119, v113
	v_max_f32_e32 v119, v62, v62
	v_max_f32_e32 v120, v54, v54
	v_max_f32_e32 v119, v120, v119
	v_max3_f32 v112, v112, v113, v119
	v_max_f32_e32 v113, v98, v98
	v_max_f32_e32 v119, v116, v116
	v_max_f32_e32 v113, v119, v113
	v_max_f32_e32 v119, v63, v63
	v_max_f32_e32 v120, v115, v115
	v_max_f32_e32 v119, v120, v119
	v_max3_f32 v112, v112, v113, v119
	v_max_f32_e32 v113, v100, v100
	v_max_f32_e32 v119, v118, v118
	v_max_f32_e32 v113, v119, v113
	v_max_f32_e32 v119, v99, v99
	v_max_f32_e32 v120, v117, v117
	v_max_f32_e32 v119, v120, v119
	v_max3_f32 v112, v112, v113, v119
	v_max_f32_e32 v113, v58, v58
	v_max_f32_e32 v119, v114, v114
	v_max_f32_e32 v113, v119, v113
	v_max_f32_e32 v119, v57, v57
	v_max_f32_e32 v120, v105, v105
	v_max_f32_e32 v119, v120, v119
	v_max3_f32 v112, v112, v113, v119
	v_max_f32_e32 v113, v61, v61
	v_max_f32_e32 v119, v108, v108
	v_max_f32_e32 v113, v119, v113
	v_max_f32_e32 v119, v60, v60
	v_max_f32_e32 v120, v106, v106
	v_max_f32_e32 v119, v120, v119
	v_max3_f32 v112, v112, v113, v119
	v_max_f32_e32 v113, v102, v102
	v_max_f32_e32 v119, v109, v109
	v_max_f32_e32 v113, v119, v113
	v_max_f32_e32 v119, v101, v101
	v_max_f32_e32 v120, v107, v107
	v_max_f32_e32 v119, v120, v119
	v_max3_f32 v112, v112, v113, v119
	v_max_f32_e32 v113, v104, v104
	v_max_f32_e32 v119, v111, v111
	v_max_f32_e32 v113, v119, v113
	v_max_f32_e32 v119, v103, v103
	v_max_f32_e32 v120, v110, v110
	v_max_f32_e32 v119, v120, v119
	v_max3_f32 v112, v112, v113, v119
	ds_bpermute_b32 v113, v185, v112
	v_log_f32_e32 v119, v18
	v_cmp_lt_f32_e32 vcc, 1.0, v18
	s_waitcnt lgkmcnt(0)
	v_max_f32_e32 v113, v113, v113
	v_max_f32_e32 v112, v112, v113
	v_cndmask_b32_e32 v113, 0, v119, vcc
	v_max3_f32 v113, v112, v113, 0
	v_exp_f32_e64 v112, -v113
	v_add_f32_e32 v51, v51, v113
	v_sub_f32_e32 v53, v53, v113
	v_sub_f32_e32 v52, v52, v113
	v_mul_f32_e32 v96, v96, v112
	v_mul_f32_e32 v97, v97, v112
	v_mul_f32_e32 v94, v94, v112
	v_mul_f32_e32 v95, v95, v112
	v_mul_f32_e32 v92, v92, v112
	v_mul_f32_e32 v93, v93, v112
	v_mul_f32_e32 v90, v90, v112
	v_mul_f32_e32 v91, v91, v112
	v_mul_f32_e32 v88, v88, v112
	v_mul_f32_e32 v89, v89, v112
	v_mul_f32_e32 v86, v86, v112
	v_mul_f32_e32 v87, v87, v112
	v_mul_f32_e32 v84, v84, v112
	v_mul_f32_e32 v85, v85, v112
	v_mul_f32_e32 v82, v82, v112
	v_mul_f32_e32 v83, v83, v112
	v_mul_f32_e32 v16, v16, v112
	v_mul_f32_e32 v17, v17, v112
	v_mul_f32_e32 v14, v14, v112
	v_mul_f32_e32 v15, v15, v112
	v_mul_f32_e32 v12, v12, v112
	v_mul_f32_e32 v13, v13, v112
	v_mul_f32_e32 v10, v10, v112
	v_mul_f32_e32 v11, v11, v112
	v_mul_f32_e32 v8, v8, v112
	v_mul_f32_e32 v9, v9, v112
	v_mul_f32_e32 v6, v6, v112
	v_mul_f32_e32 v7, v7, v112
	v_mul_f32_e32 v4, v4, v112
	v_mul_f32_e32 v5, v5, v112
	v_mul_f32_e32 v2, v2, v112
	v_mul_f32_e32 v3, v3, v112
	v_mul_f32_e32 v32, v32, v112
	v_mul_f32_e32 v33, v33, v112
	v_mul_f32_e32 v30, v30, v112
	v_mul_f32_e32 v31, v31, v112
	v_mul_f32_e32 v28, v28, v112
	v_mul_f32_e32 v29, v29, v112
	v_mul_f32_e32 v26, v26, v112
	v_mul_f32_e32 v27, v27, v112
	v_mul_f32_e32 v24, v24, v112
	v_mul_f32_e32 v25, v25, v112
	v_mul_f32_e32 v22, v22, v112
	v_mul_f32_e32 v23, v23, v112
	v_mul_f32_e32 v20, v20, v112
	v_mul_f32_e32 v21, v21, v112
	v_mul_f32_e32 v18, v18, v112
	v_mul_f32_e32 v19, v19, v112
	v_sub_f32_e32 v55, v55, v113
	v_sub_f32_e32 v54, v54, v113
	v_sub_f32_e32 v116, v116, v113
	v_sub_f32_e32 v115, v115, v113
	v_sub_f32_e32 v118, v118, v113
	v_sub_f32_e32 v117, v117, v113
	v_sub_f32_e32 v114, v114, v113
	v_sub_f32_e32 v105, v105, v113
	v_sub_f32_e32 v108, v108, v113
	v_sub_f32_e32 v106, v106, v113
	v_sub_f32_e32 v109, v109, v113
	v_sub_f32_e32 v107, v107, v113
	v_sub_f32_e32 v111, v111, v113
	v_sub_f32_e32 v110, v110, v113
	v_sub_f32_e32 v64, v64, v113
	v_sub_f32_e32 v59, v59, v113
	v_sub_f32_e32 v65, v65, v113
	v_sub_f32_e32 v62, v62, v113
	v_sub_f32_e32 v98, v98, v113
	v_sub_f32_e32 v63, v63, v113
	v_sub_f32_e32 v100, v100, v113
	v_sub_f32_e32 v99, v99, v113
	v_sub_f32_e32 v58, v58, v113
	v_sub_f32_e32 v57, v57, v113
	v_sub_f32_e32 v61, v61, v113
	v_sub_f32_e32 v60, v60, v113
	v_sub_f32_e32 v102, v102, v113
	v_sub_f32_e32 v101, v101, v113
	v_sub_f32_e32 v104, v104, v113
	v_sub_f32_e32 v103, v103, v113
; DI float ex2(float x) { return __builtin_amdgcn_exp2f(x); }
; DI f32x16 mfma(bf16x8 a, bf16x8 b, f32x16 c) { return __builtin_amdgcn_mfma_f32_32x32x16_bf16(a, b, c, 0, 0, 0); }
; template <int MODE, int KS0, int NKS>
; DI void softmax_pv(const bf16x8 (&qf)[4], const u16* Ks, const u16* Vs, float& m, f32x16& ls, f32x16& o0, f32x16& o1,
;                    float sl2, int dl, bool need_mask, bool first, int r, int h, int rs, const int (&lo)[4]) {
;     ...
; #pragma unroll
;   for (int i = 0; i < 16; ++i) { s0[i] = ex2(s0[i]); s1[i] = ex2(s1[i]); }
;   const u32x4 one4 = {0x3f803f80u, 0x3f803f80u, 0x3f803f80u, 0x3f803f80u};
;   const bf16x8 ones = __builtin_bit_cast(bf16x8, one4);
; #pragma unroll
;   for (int kk = 0; kk < 4; ++kk) {
;     const int s = kk & 1;
;     unsigned u0, u1, u2, u3;
;     if (kk < 2) {
;       u0 = pk2(s0[8 * s], s0[8 * s + 1]); u1 = pk2(s0[8 * s + 2], s0[8 * s + 3]);
;       u2 = pk2(s0[8 * s + 4], s0[8 * s + 5]); u3 = pk2(s0[8 * s + 6], s0[8 * s + 7]);
;     } else {
;       u0 = pk2(s1[8 * s], s1[8 * s + 1]); u1 = pk2(s1[8 * s + 2], s1[8 * s + 3]);
;       u2 = pk2(s1[8 * s + 4], s1[8 * s + 5]); u3 = pk2(s1[8 * s + 6], s1[8 * s + 7]);
;     }
;     u32x4 uu = {u0, u1, u2, u3};
;     bf16x8 pf = __builtin_bit_cast(bf16x8, uu);
;     bf16x8 v0 = ldsv(Vs + lo[kk]);
;     bf16x8 v1 = ldsv(Vs + 32 * rs + lo[kk]);
;     o0 = mfma(v0, pf, o0);
;     o1 = mfma(v1, pf, o1);
;     ls = mfma(ones, pf, ls);
;   }
.LBB0_328:
	v_exp_f32_e32 v112, v118
	v_exp_f32_e32 v113, v117
	v_exp_f32_e32 v120, v116
	ds_read_b128 v[116:119], v209 offset:46080
	v_exp_f32_e32 v115, v115
	v_exp_f32_e32 v55, v55
	v_exp_f32_e32 v54, v54
	v_exp_f32_e32 v53, v53
	v_exp_f32_e32 v52, v52
	v_cvt_pk_bf16_f32 v123, v112, v113
	v_cvt_pk_bf16_f32 v122, v120, v115
	v_cvt_pk_bf16_f32 v121, v55, v54
	v_cvt_pk_bf16_f32 v120, v53, v52
	v_exp_f32_e32 v112, v114
	v_exp_f32_e32 v113, v108
	s_waitcnt lgkmcnt(0)
	v_mfma_f32_32x32x16_bf16 v[82:97], v[116:119], v[120:123], v[82:97]
	v_exp_f32_e32 v114, v109
	v_exp_f32_e32 v115, v111
	v_exp_f32_e32 v116, v110
	ds_read_b128 v[108:111], v209 offset:46112
	ds_read_b128 v[52:55], v209 offset:50688
	v_exp_f32_e32 v107, v107
	v_exp_f32_e32 v106, v106
	v_exp_f32_e32 v105, v105
	v_cvt_pk_bf16_f32 v115, v115, v116
	v_cvt_pk_bf16_f32 v114, v114, v107
	v_cvt_pk_bf16_f32 v113, v113, v106
	v_cvt_pk_bf16_f32 v112, v112, v105
	s_waitcnt lgkmcnt(0)
	v_mfma_f32_32x32x16_bf16 v[2:17], v[52:55], v[120:123], v[2:17]
	s_mov_b32 s97, s96
	s_mov_b32 s98, s96
	s_mov_b32 s99, s96
	v_mov_b64_e32 v[52:53], s[96:97]
	v_mov_b64_e32 v[54:55], s[98:99]
	v_exp_f32_e32 v105, v64
	v_exp_f32_e32 v64, v98
	v_mfma_f32_32x32x16_bf16 v[82:97], v[108:111], v[112:115], v[82:97]
	ds_read_b128 v[106:109], v209 offset:50720
	v_exp_f32_e32 v110, v65
	v_exp_f32_e32 v65, v100
	v_exp_f32_e32 v98, v99
	v_exp_f32_e32 v63, v63
	v_exp_f32_e32 v62, v62
	v_exp_f32_e32 v59, v59
	s_waitcnt lgkmcnt(0)
	v_mfma_f32_32x32x16_bf16 v[2:17], v[106:109], v[112:115], v[2:17]
	ds_read_b128 v[106:109], v209 offset:46144
	v_cvt_pk_bf16_f32 v65, v65, v98
	v_cvt_pk_bf16_f32 v64, v64, v63
	v_cvt_pk_bf16_f32 v63, v110, v62
	v_cvt_pk_bf16_f32 v62, v105, v59
	v_exp_f32_e32 v59, v104
	v_exp_f32_e32 v98, v103
	v_mfma_f32_32x32x16_bf16 v[18:33], v[52:55], v[120:123], v[18:33]
	v_exp_f32_e32 v99, v102
	v_exp_f32_e32 v100, v101
	v_exp_f32_e32 v101, v61
	v_exp_f32_e32 v102, v60
	v_exp_f32_e32 v58, v58
	v_exp_f32_e32 v57, v57
	v_cvt_pk_bf16_f32 v61, v59, v98
	s_waitcnt lgkmcnt(0)
	v_mfma_f32_32x32x16_bf16 v[82:97], v[106:109], v[62:65], v[82:97]
	ds_read_b128 v[106:109], v209 offset:50752
	v_cvt_pk_bf16_f32 v60, v99, v100
	v_cvt_pk_bf16_f32 v59, v101, v102
	v_cvt_pk_bf16_f32 v58, v58, v57
	v_readlane_b32 s97, v250, 29
	v_mfma_f32_32x32x16_bf16 v[18:33], v[52:55], v[112:115], v[18:33]
	s_waitcnt lgkmcnt(0)
	v_mfma_f32_32x32x16_bf16 v[2:17], v[106:109], v[62:65], v[2:17]
	v_mfma_f32_32x32x16_bf16 v[18:33], v[52:55], v[62:65], v[18:33]
	ds_read_b128 v[232:235], v209 offset:46176
	ds_read_b128 v[62:65], v209 offset:50784
	s_waitcnt lgkmcnt(1)
	v_mfma_f32_32x32x16_bf16 v[82:97], v[232:235], v[58:61], v[82:97]
	s_waitcnt lgkmcnt(0)
	v_mfma_f32_32x32x16_bf16 v[2:17], v[62:65], v[58:61], v[2:17]
	v_mfma_f32_32x32x16_bf16 v[18:33], v[52:55], v[58:61], v[18:33]
	s_or_b64 exec, exec, s[0:1]
	s_and_saveexec_b64 s[0:1], s[6:7]
	s_cbranch_execz .LBB0_339
	s_branch .LBB0_336

; DI f32x16 mfma(bf16x8 a, bf16x8 b, f32x16 c) { return __builtin_amdgcn_mfma_f32_32x32x16_bf16(a, b, c, 0, 0, 0); }
; template <int MODE, int KS0, int NKS>
; DI void qk_scores(f32x16& s0, f32x16& s1, const u16* Ks, const bf16x8 (&qf)[4], float sl2, int dl, float mref,
;                   bool need_mask, int r, int h, int rs, const int (&lo)[4]) {
;     ...
;   const float nb = -sl2 * (float)dl - mref;
; #pragma unroll
;   for (int i = 0; i < 16; ++i) {
;     const int ci = (i & 3) + 8 * (i >> 2);
;     s0[i] = fmaf(sl2, (float)ci, nb);
;     s1[i] = fmaf(sl2, (float)(ci + 32), nb);
;   }
; #pragma unroll
;   for (int ks = 0; ks < NKS; ++ks) {
;     bf16x8 k0 = ldsv(Ks + lo[KS0 + ks]);
;     bf16x8 k1 = ldsv(Ks + 32 * rs + lo[KS0 + ks]);
;     s0 = mfma(k0, qf[KS0 + ks], s0);
;     s1 = mfma(k1, qf[KS0 + ks], s1);
;   }
;   if (need_mask) {
; #pragma unroll
;     for (int i = 0; i < 16; ++i) {
;       const int ci = (i & 3) + 8 * (i >> 2);
;       bool v0 = (MODE == 0) ? (ci <= dl) : (ci <= dl && ci > dl - 128);
;       bool v1 = (MODE == 0) ? (ci + 32 <= dl) : (ci + 32 <= dl && ci + 32 > dl - 128);
;       s0[i] = v0 ? s0[i] : -INFINITY;
;       s1[i] = v1 ? s1[i] : -INFINITY;
;     }
;   }
; DI void attn_item_B2(const Params& p, int layer, int b, int head0, int qblk, u16* sm, int wv) {
;     ...
;         const bool skip = (k0 > q0w + 31) || (k0 + 63 < q0w - 127);
;         if (!skip) {
;           const int dl = qpos - k0 - 4 * h;
.LBB0_330:
	v_cmp_le_i32_e32 vcc, v217, v210
	v_cmp_ge_i32_e64 s[2:3], v218, v211
	s_and_b64 s[18:19], vcc, s[2:3]
	s_and_saveexec_b64 s[2:3], s[18:19]
	s_cbranch_execz .LBB0_334
	v_add3_u32 v186, v221, v208, 64
	s_mov_b32 s18, 2.0
	v_cvt_f32_i32_e32 v57, v186
	s_mov_b32 s19, 0x40400000
	ds_read_b128 v[52:55], v209 offset:18432
	ds_read_b128 v[58:61], v209 offset:23040
	v_fma_f32 v62, -v56, v57, -v51
	v_fma_f32 v100, v56, s18, v62
	v_fma_f32 v101, v56, s19, v62
	s_mov_b32 s18, 0x41000000
	s_mov_b32 s19, 0x41100000
	v_fma_f32 v102, v56, s18, v62
	v_fma_f32 v103, v56, s19, v62
	s_mov_b32 s18, 0x41200000
	s_mov_b32 s19, 0x41300000
	v_fma_f32 v104, v56, s18, v62
	v_fma_f32 v105, v56, s19, v62
	s_mov_b32 s18, 0x41800000
	s_mov_b32 s19, 0x41880000
	v_fma_f32 v106, v56, s18, v62
	v_fma_f32 v107, v56, s19, v62
	s_mov_b32 s18, 0x41900000
	s_mov_b32 s19, 0x41980000
	v_fma_f32 v98, 0, v56, v62
	v_add_f32_e32 v99, v56, v62
	v_fma_f32 v108, v56, s18, v62
	v_fma_f32 v109, v56, s19, v62
	v_fma_f32 v110, v56, s50, v62
	v_fma_f32 v111, v56, s51, v62
	v_fma_f32 v112, v56, s28, v62
	v_fma_f32 v113, v56, s29, v62
	s_mov_b32 s18, 0x42680000
	s_mov_b32 s19, 0x426c0000
	s_waitcnt lgkmcnt(1)
	v_mfma_f32_32x32x16_bf16 v[98:113], v[52:55], v[142:145], v[98:113]
	ds_read_b128 v[52:55], v209 offset:18464
	v_fma_f32 v128, v56, s18, v62
	v_fma_f32 v129, v56, s19, v62
	s_mov_b32 s18, 0x42400000
	s_mov_b32 s19, 0x42440000
	v_fma_f32 v126, v56, s30, v62
	v_fma_f32 v127, v56, s31, v62
	v_fma_f32 v124, v56, s10, v62
	v_fma_f32 v125, v56, s11, v62
	v_fma_f32 v122, v56, s18, v62
	v_fma_f32 v123, v56, s19, v62
	v_fma_f32 v120, v56, s72, v62
	v_fma_f32 v121, v56, s73, v62
	v_fma_f32 v118, v56, s74, v62
	v_fma_f32 v119, v56, s75, v62
	v_fma_f32 v116, v56, s76, v62
	v_fma_f32 v117, v56, s77, v62
	v_fma_f32 v114, v56, s78, v62
	v_fma_f32 v115, v56, s79, v62
	s_waitcnt lgkmcnt(0)
	v_mfma_f32_32x32x16_bf16 v[98:113], v[52:55], v[138:141], v[98:113]
	ds_read_b128 v[52:55], v209 offset:23072
	v_add_u32_e32 v57, -1, v186
	v_cmp_gt_u32_e32 vcc, s95, v57
	v_subrev_u32_e32 v57, 35, v186
	v_mfma_f32_32x32x16_bf16 v[114:129], v[58:61], v[142:145], v[114:129]
	s_waitcnt lgkmcnt(0)
	v_mfma_f32_32x32x16_bf16 v[114:129], v[52:55], v[138:141], v[114:129]
	ds_read_b128 v[232:235], v209 offset:18496
	ds_read_b128 v[52:55], v209 offset:23104
	s_waitcnt lgkmcnt(1)
	v_mfma_f32_32x32x16_bf16 v[98:113], v[232:235], v[134:137], v[98:113]
	s_waitcnt lgkmcnt(0)
	v_mfma_f32_32x32x16_bf16 v[114:129], v[52:55], v[134:137], v[114:129]
	ds_read_b128 v[52:55], v209 offset:18528
	ds_read_b128 v[58:61], v209 offset:23136
	s_waitcnt lgkmcnt(1)
	v_mfma_f32_32x32x16_bf16 v[98:113], v[52:55], v[130:133], v[98:113]
	v_subrev_u32_e32 v54, 33, v186
	v_subrev_u32_e32 v55, 32, v186
	s_waitcnt lgkmcnt(0)
	v_mfma_f32_32x32x16_bf16 v[114:129], v[58:61], v[130:133], v[114:129]
	s_nop 7
	v_cndmask_b32_e32 v52, v199, v99, vcc
	v_cmp_gt_u32_e32 vcc, s95, v186
	v_subrev_u32_e32 v58, 34, v186
	v_subrev_u32_e32 v60, 19, v186
	v_cndmask_b32_e32 v53, v199, v98, vcc
	v_cmp_gt_u32_e32 vcc, s95, v54
	v_add_u32_e32 v54, -3, v186
	v_subrev_u32_e32 v61, 18, v186
	v_cndmask_b32_e32 v59, v199, v115, vcc
	v_cmp_gt_u32_e32 vcc, s95, v55
	v_add_u32_e32 v55, -2, v186
	s_nop 0
	v_cndmask_b32_e32 v64, v199, v114, vcc
	v_cmp_gt_u32_e32 vcc, s95, v54
	s_nop 1
	v_cndmask_b32_e32 v54, v199, v101, vcc
	v_cmp_gt_u32_e32 vcc, s95, v55
	v_subrev_u32_e32 v101, 25, v186
	s_nop 0
	v_cndmask_b32_e32 v55, v199, v100, vcc
	v_cmp_gt_u32_e32 vcc, s95, v57
	v_add_u32_e32 v57, -9, v186
	s_nop 0
	v_cndmask_b32_e32 v62, v199, v117, vcc
	v_cmp_gt_u32_e32 vcc, s95, v58
	v_add_u32_e32 v58, -8, v186
	s_nop 0
	v_cndmask_b32_e32 v65, v199, v116, vcc
	v_cmp_gt_u32_e32 vcc, s95, v57
	v_subrev_u32_e32 v57, 41, v186
	s_nop 0
	v_cndmask_b32_e32 v115, v199, v103, vcc
	v_cmp_gt_u32_e32 vcc, s95, v58
	v_subrev_u32_e32 v58, 40, v186
	v_subrev_u32_e32 v103, 27, v186
	v_cndmask_b32_e32 v116, v199, v102, vcc
	v_cmp_gt_u32_e32 vcc, s95, v57
	v_add_u32_e32 v57, -11, v186
	v_subrev_u32_e32 v102, 24, v186
	v_cndmask_b32_e32 v63, v199, v119, vcc
	v_cmp_gt_u32_e32 vcc, s95, v58
	v_add_u32_e32 v58, -10, v186
	s_nop 0
	v_cndmask_b32_e32 v98, v199, v118, vcc
	v_cmp_gt_u32_e32 vcc, s95, v57
	v_subrev_u32_e32 v57, 43, v186
	s_nop 0
	v_cndmask_b32_e32 v117, v199, v105, vcc
	v_cmp_gt_u32_e32 vcc, s95, v58
	v_subrev_u32_e32 v58, 42, v186
	s_nop 0
	v_cndmask_b32_e32 v118, v199, v104, vcc
	v_cmp_gt_u32_e32 vcc, s95, v57
	v_subrev_u32_e32 v57, 17, v186
	v_subrev_u32_e32 v104, 26, v186
	v_cndmask_b32_e32 v99, v199, v121, vcc
	v_cmp_gt_u32_e32 vcc, s95, v58
	v_add_u32_e32 v58, -16, v186
	s_nop 0
	v_cndmask_b32_e32 v100, v199, v120, vcc
	v_cmp_gt_u32_e32 vcc, s95, v57
	v_subrev_u32_e32 v57, 49, v186
	s_nop 0
	v_cndmask_b32_e32 v105, v199, v107, vcc
	v_cmp_gt_u32_e32 vcc, s95, v58
	v_subrev_u32_e32 v58, 48, v186
	s_nop 0
	v_cndmask_b32_e32 v114, v199, v106, vcc
	v_cmp_gt_u32_e32 vcc, s95, v57
	s_nop 1
	v_cndmask_b32_e32 v57, v199, v123, vcc
	v_cmp_gt_u32_e32 vcc, s95, v58
	s_nop 1
	v_cndmask_b32_e32 v58, v199, v122, vcc
	v_cmp_gt_u32_e32 vcc, s95, v60
	v_subrev_u32_e32 v60, 51, v186
	s_nop 0
	v_cndmask_b32_e32 v106, v199, v109, vcc
	v_cmp_gt_u32_e32 vcc, s95, v61
	v_subrev_u32_e32 v61, 50, v186
	s_nop 0
	v_cndmask_b32_e32 v108, v199, v108, vcc
	v_cmp_gt_u32_e32 vcc, s95, v60
	s_nop 1
	v_cndmask_b32_e32 v60, v199, v125, vcc
	v_cmp_gt_u32_e32 vcc, s95, v61
	s_nop 1
	v_cndmask_b32_e32 v61, v199, v124, vcc
	v_cmp_gt_u32_e32 vcc, s95, v101
	v_subrev_u32_e32 v101, 57, v186
	s_nop 0
	v_cndmask_b32_e32 v107, v199, v111, vcc
	v_cmp_gt_u32_e32 vcc, s95, v102
	v_subrev_u32_e32 v102, 56, v186
	s_nop 0
	v_cndmask_b32_e32 v109, v199, v110, vcc
	v_cmp_gt_u32_e32 vcc, s95, v101
	s_nop 1
	v_cndmask_b32_e32 v101, v199, v127, vcc
	v_cmp_gt_u32_e32 vcc, s95, v102
	s_nop 1
	v_cndmask_b32_e32 v102, v199, v126, vcc
	v_cmp_gt_u32_e32 vcc, s95, v103
	v_subrev_u32_e32 v103, 59, v186
	s_nop 0
	v_cndmask_b32_e32 v110, v199, v113, vcc
	v_cmp_gt_u32_e32 vcc, s95, v104
	v_subrev_u32_e32 v104, 58, v186
	s_nop 0
	v_cndmask_b32_e32 v111, v199, v112, vcc
	v_cmp_gt_u32_e32 vcc, s95, v103
	s_nop 1
	v_cndmask_b32_e32 v103, v199, v129, vcc
	v_cmp_gt_u32_e32 vcc, s95, v104
	s_nop 1
	v_cndmask_b32_e32 v104, v199, v128, vcc
	v_cmp_nge_f32_e32 vcc, s9, v18
	s_cbranch_vccz .LBB0_333
; DI float ex2(float x) { return __builtin_amdgcn_exp2f(x); }
; DI float lg2(float x) { return __builtin_amdgcn_logf(x); }
; template <int MODE, int KS0, int NKS>
; DI void softmax_pv(const bf16x8 (&qf)[4], const u16* Ks, const u16* Vs, float& m, f32x16& ls, f32x16& o0, f32x16& o1,
;                    float sl2, int dl, bool need_mask, bool first, int r, int h, int rs, const int (&lo)[4]) {
;     ...
;   if (__any(first || !(ls[0] <= 1.0e12f))) {
;     float tmax = -INFINITY;
; #pragma unroll
;     for (int i = 0; i < 16; ++i) tmax = fmaxf(tmax, fmaxf(s0[i], s1[i]));
;     tmax = fmaxf(tmax, shx(tmax, r + 32 * h));
;     const float lref = (ls[0] > 1.f) ? lg2(ls[0]) : 0.f;
;     const float delta = first ? tmax : fmaxf(fmaxf(tmax, lref), 0.f);
;     m += delta;
;     const float alpha = ex2(-delta);
; #pragma unroll
;     for (int e = 0; e < 16; ++e) { o0[e] *= alpha; o1[e] *= alpha; ls[e] *= alpha; }
; #pragma unroll
;     for (int i = 0; i < 16; ++i) { s0[i] -= delta; s1[i] -= delta; }
;   }
	v_max_f32_e32 v112, v64, v64
	v_max_f32_e32 v113, v53, v53
	v_max_f32_e32 v112, v113, v112
	v_max_f32_e32 v113, v59, v59
	v_max_f32_e32 v119, v52, v52
	v_max_f32_e32 v113, v119, v113
	s_mov_b32 s18, 0xff800000
	v_max3_f32 v112, v112, s18, v113
	v_max_f32_e32 v113, v65, v65
	v_max_f32_e32 v119, v55, v55
	v_max_f32_e32 v113, v119, v113
	v_max_f32_e32 v119, v62, v62
	v_max_f32_e32 v120, v54, v54
	v_max_f32_e32 v119, v120, v119
	v_max3_f32 v112, v112, v113, v119
	v_max_f32_e32 v113, v98, v98
	v_max_f32_e32 v119, v116, v116
	v_max_f32_e32 v113, v119, v113
	v_max_f32_e32 v119, v63, v63
	v_max_f32_e32 v120, v115, v115
	v_max_f32_e32 v119, v120, v119
	v_max3_f32 v112, v112, v113, v119
	v_max_f32_e32 v113, v100, v100
	v_max_f32_e32 v119, v118, v118
	v_max_f32_e32 v113, v119, v113
	v_max_f32_e32 v119, v99, v99
	v_max_f32_e32 v120, v117, v117
	v_max_f32_e32 v119, v120, v119
	v_max3_f32 v112, v112, v113, v119
	v_max_f32_e32 v113, v58, v58
	v_max_f32_e32 v119, v114, v114
	v_max_f32_e32 v113, v119, v113
	v_max_f32_e32 v119, v57, v57
	v_max_f32_e32 v120, v105, v105
	v_max_f32_e32 v119, v120, v119
	v_max3_f32 v112, v112, v113, v119
	v_max_f32_e32 v113, v61, v61
	v_max_f32_e32 v119, v108, v108
	v_max_f32_e32 v113, v119, v113
	v_max_f32_e32 v119, v60, v60
	v_max_f32_e32 v120, v106, v106
	v_max_f32_e32 v119, v120, v119
	v_max3_f32 v112, v112, v113, v119
	v_max_f32_e32 v113, v102, v102
	v_max_f32_e32 v119, v109, v109
	v_max_f32_e32 v113, v119, v113
	v_max_f32_e32 v119, v101, v101
	v_max_f32_e32 v120, v107, v107
	v_max_f32_e32 v119, v120, v119
	v_max3_f32 v112, v112, v113, v119
	v_max_f32_e32 v113, v104, v104
	v_max_f32_e32 v119, v111, v111
	v_max_f32_e32 v113, v119, v113
	v_max_f32_e32 v119, v103, v103
	v_max_f32_e32 v120, v110, v110
	v_max_f32_e32 v119, v120, v119
	v_max3_f32 v112, v112, v113, v119
	ds_bpermute_b32 v113, v185, v112
	v_log_f32_e32 v119, v18
	v_cmp_lt_f32_e32 vcc, 1.0, v18
	s_waitcnt lgkmcnt(0)
	v_max_f32_e32 v113, v113, v113
	v_max_f32_e32 v112, v112, v113
	v_cndmask_b32_e32 v113, 0, v119, vcc
	v_max3_f32 v113, v112, v113, 0
	v_exp_f32_e64 v112, -v113
	v_add_f32_e32 v51, v51, v113
	v_sub_f32_e32 v53, v53, v113
	v_sub_f32_e32 v52, v52, v113
	v_mul_f32_e32 v96, v96, v112
	v_mul_f32_e32 v97, v97, v112
	v_mul_f32_e32 v94, v94, v112
	v_mul_f32_e32 v95, v95, v112
	v_mul_f32_e32 v92, v92, v112
	v_mul_f32_e32 v93, v93, v112
	v_mul_f32_e32 v90, v90, v112
	v_mul_f32_e32 v91, v91, v112
	v_mul_f32_e32 v88, v88, v112
	v_mul_f32_e32 v89, v89, v112
	v_mul_f32_e32 v86, v86, v112
	v_mul_f32_e32 v87, v87, v112
	v_mul_f32_e32 v84, v84, v112
	v_mul_f32_e32 v85, v85, v112
	v_mul_f32_e32 v82, v82, v112
	v_mul_f32_e32 v83, v83, v112
	v_mul_f32_e32 v16, v16, v112
	v_mul_f32_e32 v17, v17, v112
	v_mul_f32_e32 v14, v14, v112
	v_mul_f32_e32 v15, v15, v112
	v_mul_f32_e32 v12, v12, v112
	v_mul_f32_e32 v13, v13, v112
	v_mul_f32_e32 v10, v10, v112
	v_mul_f32_e32 v11, v11, v112
	v_mul_f32_e32 v8, v8, v112
	v_mul_f32_e32 v9, v9, v112
	v_mul_f32_e32 v6, v6, v112
	v_mul_f32_e32 v7, v7, v112
	v_mul_f32_e32 v4, v4, v112
	v_mul_f32_e32 v5, v5, v112
	v_mul_f32_e32 v2, v2, v112
	v_mul_f32_e32 v3, v3, v112
	v_mul_f32_e32 v32, v32, v112
	v_mul_f32_e32 v33, v33, v112
	v_mul_f32_e32 v30, v30, v112
	v_mul_f32_e32 v31, v31, v112
	v_mul_f32_e32 v28, v28, v112
	v_mul_f32_e32 v29, v29, v112
	v_mul_f32_e32 v26, v26, v112
	v_mul_f32_e32 v27, v27, v112
	v_mul_f32_e32 v24, v24, v112
	v_mul_f32_e32 v25, v25, v112
	v_mul_f32_e32 v22, v22, v112
	v_mul_f32_e32 v23, v23, v112
	v_mul_f32_e32 v20, v20, v112
	v_mul_f32_e32 v21, v21, v112
	v_mul_f32_e32 v18, v18, v112
	v_mul_f32_e32 v19, v19, v112
	v_sub_f32_e32 v55, v55, v113
	v_sub_f32_e32 v54, v54, v113
	v_sub_f32_e32 v116, v116, v113
	v_sub_f32_e32 v115, v115, v113
	v_sub_f32_e32 v118, v118, v113
	v_sub_f32_e32 v117, v117, v113
	v_sub_f32_e32 v114, v114, v113
	v_sub_f32_e32 v105, v105, v113
	v_sub_f32_e32 v108, v108, v113
	v_sub_f32_e32 v106, v106, v113
	v_sub_f32_e32 v109, v109, v113
	v_sub_f32_e32 v107, v107, v113
	v_sub_f32_e32 v111, v111, v113
	v_sub_f32_e32 v110, v110, v113
	v_sub_f32_e32 v64, v64, v113
	v_sub_f32_e32 v59, v59, v113
	v_sub_f32_e32 v65, v65, v113
	v_sub_f32_e32 v62, v62, v113
	v_sub_f32_e32 v98, v98, v113
	v_sub_f32_e32 v63, v63, v113
	v_sub_f32_e32 v100, v100, v113
	v_sub_f32_e32 v99, v99, v113
	v_sub_f32_e32 v58, v58, v113
	v_sub_f32_e32 v57, v57, v113
	v_sub_f32_e32 v61, v61, v113
	v_sub_f32_e32 v60, v60, v113
	v_sub_f32_e32 v102, v102, v113
	v_sub_f32_e32 v101, v101, v113
	v_sub_f32_e32 v104, v104, v113
	v_sub_f32_e32 v103, v103, v113
; DI float ex2(float x) { return __builtin_amdgcn_exp2f(x); }
; DI f32x16 mfma(bf16x8 a, bf16x8 b, f32x16 c) { return __builtin_amdgcn_mfma_f32_32x32x16_bf16(a, b, c, 0, 0, 0); }
; template <int MODE, int KS0, int NKS>
; DI void softmax_pv(const bf16x8 (&qf)[4], const u16* Ks, const u16* Vs, float& m, f32x16& ls, f32x16& o0, f32x16& o1,
;                    float sl2, int dl, bool need_mask, bool first, int r, int h, int rs, const int (&lo)[4]) {
;     ...
; #pragma unroll
;   for (int i = 0; i < 16; ++i) { s0[i] = ex2(s0[i]); s1[i] = ex2(s1[i]); }
;   const u32x4 one4 = {0x3f803f80u, 0x3f803f80u, 0x3f803f80u, 0x3f803f80u};
;   const bf16x8 ones = __builtin_bit_cast(bf16x8, one4);
; #pragma unroll
;   for (int kk = 0; kk < 4; ++kk) {
;     const int s = kk & 1;
;     unsigned u0, u1, u2, u3;
;     if (kk < 2) {
;       u0 = pk2(s0[8 * s], s0[8 * s + 1]); u1 = pk2(s0[8 * s + 2], s0[8 * s + 3]);
;       u2 = pk2(s0[8 * s + 4], s0[8 * s + 5]); u3 = pk2(s0[8 * s + 6], s0[8 * s + 7]);
;     } else {
;       u0 = pk2(s1[8 * s], s1[8 * s + 1]); u1 = pk2(s1[8 * s + 2], s1[8 * s + 3]);
;       u2 = pk2(s1[8 * s + 4], s1[8 * s + 5]); u3 = pk2(s1[8 * s + 6], s1[8 * s + 7]);
;     }
;     u32x4 uu = {u0, u1, u2, u3};
;     bf16x8 pf = __builtin_bit_cast(bf16x8, uu);
;     bf16x8 v0 = ldsv(Vs + lo[kk]);
;     bf16x8 v1 = ldsv(Vs + 32 * rs + lo[kk]);
;     o0 = mfma(v0, pf, o0);
;     o1 = mfma(v1, pf, o1);
;     ls = mfma(ones, pf, ls);
;   }
.LBB0_333:
	v_exp_f32_e32 v112, v118
	v_exp_f32_e32 v113, v117
	v_exp_f32_e32 v120, v116
	ds_read_b128 v[116:119], v209 offset:27648
	v_exp_f32_e32 v115, v115
	v_exp_f32_e32 v55, v55
	v_exp_f32_e32 v54, v54
	v_exp_f32_e32 v53, v53
	v_exp_f32_e32 v52, v52
	v_cvt_pk_bf16_f32 v123, v112, v113
	v_cvt_pk_bf16_f32 v122, v120, v115
	v_cvt_pk_bf16_f32 v121, v55, v54
	v_cvt_pk_bf16_f32 v120, v53, v52
	v_exp_f32_e32 v112, v114
	v_exp_f32_e32 v113, v108
	s_waitcnt lgkmcnt(0)
	v_mfma_f32_32x32x16_bf16 v[82:97], v[116:119], v[120:123], v[82:97]
	v_exp_f32_e32 v114, v109
	v_exp_f32_e32 v115, v111
	v_exp_f32_e32 v116, v110
	ds_read_b128 v[108:111], v209 offset:27680
	ds_read_b128 v[52:55], v209 offset:32256
	v_exp_f32_e32 v107, v107
	v_exp_f32_e32 v106, v106
	v_exp_f32_e32 v105, v105
	v_cvt_pk_bf16_f32 v115, v115, v116
	v_cvt_pk_bf16_f32 v114, v114, v107
	v_cvt_pk_bf16_f32 v113, v113, v106
	v_cvt_pk_bf16_f32 v112, v112, v105
	s_waitcnt lgkmcnt(0)
	v_mfma_f32_32x32x16_bf16 v[2:17], v[52:55], v[120:123], v[2:17]
	s_mov_b32 s97, s96
	s_mov_b32 s98, s96
	s_mov_b32 s99, s96
	v_mov_b64_e32 v[52:53], s[96:97]
	v_mov_b64_e32 v[54:55], s[98:99]
	v_exp_f32_e32 v105, v64
	v_exp_f32_e32 v64, v98
	v_mfma_f32_32x32x16_bf16 v[82:97], v[108:111], v[112:115], v[82:97]
	ds_read_b128 v[106:109], v209 offset:32288
	v_exp_f32_e32 v110, v65
	v_exp_f32_e32 v65, v100
	v_exp_f32_e32 v98, v99
	v_exp_f32_e32 v63, v63
	v_exp_f32_e32 v62, v62
	v_exp_f32_e32 v59, v59
	s_waitcnt lgkmcnt(0)
	v_mfma_f32_32x32x16_bf16 v[2:17], v[106:109], v[112:115], v[2:17]
	ds_read_b128 v[106:109], v209 offset:27712
	v_cvt_pk_bf16_f32 v65, v65, v98
	v_cvt_pk_bf16_f32 v64, v64, v63
	v_cvt_pk_bf16_f32 v63, v110, v62
	v_cvt_pk_bf16_f32 v62, v105, v59
	v_exp_f32_e32 v59, v104
	v_exp_f32_e32 v98, v103
	v_mfma_f32_32x32x16_bf16 v[18:33], v[52:55], v[120:123], v[18:33]
	v_exp_f32_e32 v99, v102
	v_exp_f32_e32 v100, v101
	v_exp_f32_e32 v101, v61
	v_exp_f32_e32 v102, v60
	v_exp_f32_e32 v58, v58
	v_exp_f32_e32 v57, v57
	v_cvt_pk_bf16_f32 v61, v59, v98
	s_waitcnt lgkmcnt(0)
	v_mfma_f32_32x32x16_bf16 v[82:97], v[106:109], v[62:65], v[82:97]
	ds_read_b128 v[106:109], v209 offset:32320
	v_cvt_pk_bf16_f32 v60, v99, v100
	v_cvt_pk_bf16_f32 v59, v101, v102
	v_cvt_pk_bf16_f32 v58, v58, v57
	v_readlane_b32 s97, v250, 29
	v_mfma_f32_32x32x16_bf16 v[18:33], v[52:55], v[112:115], v[18:33]
	s_waitcnt lgkmcnt(0)
	v_mfma_f32_32x32x16_bf16 v[2:17], v[106:109], v[62:65], v[2:17]
	v_mfma_f32_32x32x16_bf16 v[18:33], v[52:55], v[62:65], v[18:33]
	ds_read_b128 v[232:235], v209 offset:27744
	ds_read_b128 v[62:65], v209 offset:32352
	s_waitcnt lgkmcnt(1)
	v_mfma_f32_32x32x16_bf16 v[82:97], v[232:235], v[58:61], v[82:97]
	s_waitcnt lgkmcnt(0)
	v_mfma_f32_32x32x16_bf16 v[2:17], v[62:65], v[58:61], v[2:17]
	v_mfma_f32_32x32x16_bf16 v[18:33], v[52:55], v[58:61], v[18:33]

; DI f32x16 mfma(bf16x8 a, bf16x8 b, f32x16 c) { return __builtin_amdgcn_mfma_f32_32x32x16_bf16(a, b, c, 0, 0, 0); }
; template <int MODE, int KS0, int NKS>
; DI void qk_scores(f32x16& s0, f32x16& s1, const u16* Ks, const bf16x8 (&qf)[4], float sl2, int dl, float mref,
;                   bool need_mask, int r, int h, int rs, const int (&lo)[4]) {
;     ...
;   const float nb = -sl2 * (float)dl - mref;
; #pragma unroll
;   for (int i = 0; i < 16; ++i) {
;     const int ci = (i & 3) + 8 * (i >> 2);
;     s0[i] = fmaf(sl2, (float)ci, nb);
;     s1[i] = fmaf(sl2, (float)(ci + 32), nb);
;   }
; #pragma unroll
;   for (int ks = 0; ks < NKS; ++ks) {
;     bf16x8 k0 = ldsv(Ks + lo[KS0 + ks]);
;     bf16x8 k1 = ldsv(Ks + 32 * rs + lo[KS0 + ks]);
;     s0 = mfma(k0, qf[KS0 + ks], s0);
;     s1 = mfma(k1, qf[KS0 + ks], s1);
;   }
;   if (need_mask) {
; #pragma unroll
;     for (int i = 0; i < 16; ++i) {
;       const int ci = (i & 3) + 8 * (i >> 2);
;       bool v0 = (MODE == 0) ? (ci <= dl) : (ci <= dl && ci > dl - 128);
;       bool v1 = (MODE == 0) ? (ci + 32 <= dl) : (ci + 32 <= dl && ci + 32 > dl - 128);
;       s0[i] = v0 ? s0[i] : -INFINITY;
;       s1[i] = v1 ? s1[i] : -INFINITY;
;     }
;   }
.LBB0_336:
	s_mov_b32 s2, 2.0
	v_cvt_f32_i32_e32 v57, v184
	s_mov_b32 s3, 0x40400000
	ds_read_b128 v[52:55], v209 offset:55296
	ds_read_b128 v[58:61], v209 offset:59904
	v_fma_f32 v62, -v56, v57, -v51
	v_fma_f32 v100, v56, s2, v62
	v_fma_f32 v101, v56, s3, v62
	s_mov_b32 s2, 0x41000000
	s_mov_b32 s3, 0x41100000
	v_fma_f32 v102, v56, s2, v62
	v_fma_f32 v103, v56, s3, v62
	s_mov_b32 s2, 0x41200000
	s_mov_b32 s3, 0x41300000
	v_fma_f32 v104, v56, s2, v62
	v_fma_f32 v105, v56, s3, v62
	s_mov_b32 s2, 0x41800000
	s_mov_b32 s3, 0x41880000
	v_fma_f32 v106, v56, s2, v62
	v_fma_f32 v107, v56, s3, v62
	s_mov_b32 s2, 0x41900000
	s_mov_b32 s3, 0x41980000
	v_fma_f32 v98, 0, v56, v62
	v_add_f32_e32 v99, v56, v62
	v_fma_f32 v108, v56, s2, v62
	v_fma_f32 v109, v56, s3, v62
	v_fma_f32 v110, v56, s50, v62
	v_fma_f32 v111, v56, s51, v62
	v_fma_f32 v112, v56, s28, v62
	v_fma_f32 v113, v56, s29, v62
	s_mov_b32 s2, 0x42680000
	s_mov_b32 s3, 0x426c0000
	s_waitcnt lgkmcnt(1)
	v_mfma_f32_32x32x16_bf16 v[98:113], v[52:55], v[142:145], v[98:113]
	ds_read_b128 v[52:55], v209 offset:55328
	v_fma_f32 v128, v56, s2, v62
	v_fma_f32 v129, v56, s3, v62
	s_mov_b32 s2, 0x42400000
	s_mov_b32 s3, 0x42440000
	v_fma_f32 v126, v56, s30, v62
	v_fma_f32 v127, v56, s31, v62
	v_fma_f32 v124, v56, s10, v62
	v_fma_f32 v125, v56, s11, v62
	v_fma_f32 v122, v56, s2, v62
	v_fma_f32 v123, v56, s3, v62
	v_fma_f32 v120, v56, s72, v62
	v_fma_f32 v121, v56, s73, v62
	v_fma_f32 v118, v56, s74, v62
	v_fma_f32 v119, v56, s75, v62
	v_fma_f32 v116, v56, s76, v62
	v_fma_f32 v117, v56, s77, v62
	v_fma_f32 v114, v56, s78, v62
	v_fma_f32 v115, v56, s79, v62
	s_waitcnt lgkmcnt(0)
	v_mfma_f32_32x32x16_bf16 v[98:113], v[52:55], v[138:141], v[98:113]
	ds_read_b128 v[52:55], v209 offset:59936
	v_add_u32_e32 v51, -1, v184
	v_cmp_gt_u32_e32 vcc, s95, v51
	v_subrev_u32_e32 v51, 33, v184
	v_subrev_u32_e32 v63, 25, v184
	v_subrev_u32_e32 v64, 24, v184
	v_subrev_u32_e32 v65, 27, v184
	v_mfma_f32_32x32x16_bf16 v[114:129], v[58:61], v[142:145], v[114:129]
	s_waitcnt lgkmcnt(0)
	v_mfma_f32_32x32x16_bf16 v[114:129], v[52:55], v[138:141], v[114:129]
	ds_read_b128 v[232:235], v209 offset:55360
	ds_read_b128 v[52:55], v209 offset:59968
	s_waitcnt lgkmcnt(1)
	v_mfma_f32_32x32x16_bf16 v[98:113], v[232:235], v[134:137], v[98:113]
	s_waitcnt lgkmcnt(0)
	v_mfma_f32_32x32x16_bf16 v[114:129], v[52:55], v[134:137], v[114:129]
	ds_read_b128 v[52:55], v209 offset:55392
	ds_read_b128 v[56:59], v209 offset:60000
	s_waitcnt lgkmcnt(1)
	v_mfma_f32_32x32x16_bf16 v[98:113], v[52:55], v[130:133], v[98:113]
	v_subrev_u32_e32 v52, 32, v184
	v_subrev_u32_e32 v54, 19, v184
	v_subrev_u32_e32 v55, 18, v184
	s_waitcnt lgkmcnt(0)
	v_mfma_f32_32x32x16_bf16 v[114:129], v[56:59], v[130:133], v[114:129]
	s_nop 6
	v_cndmask_b32_e32 v99, v199, v99, vcc
	v_cmp_gt_u32_e32 vcc, s95, v184
	s_nop 1
	v_cndmask_b32_e32 v134, v199, v98, vcc
	v_cmp_gt_u32_e32 vcc, s95, v51
	v_add_u32_e32 v51, -3, v184
	v_subrev_u32_e32 v98, 26, v184
	v_cndmask_b32_e32 v53, v199, v115, vcc
	v_cmp_gt_u32_e32 vcc, s95, v52
	v_add_u32_e32 v52, -2, v184
	s_nop 0
	v_cndmask_b32_e32 v58, v199, v114, vcc
	v_cmp_gt_u32_e32 vcc, s95, v51
	v_subrev_u32_e32 v51, 35, v184
	s_nop 0
	v_cndmask_b32_e32 v101, v199, v101, vcc
	v_cmp_gt_u32_e32 vcc, s95, v52
	v_subrev_u32_e32 v52, 34, v184
	s_nop 0
	v_cndmask_b32_e32 v114, v199, v100, vcc
	v_cmp_gt_u32_e32 vcc, s95, v51
	v_add_u32_e32 v51, -9, v184
	s_nop 0
	v_cndmask_b32_e32 v56, v199, v117, vcc
	v_cmp_gt_u32_e32 vcc, s95, v52
	v_add_u32_e32 v52, -8, v184
	s_nop 0
	v_cndmask_b32_e32 v59, v199, v116, vcc
	v_cmp_gt_u32_e32 vcc, s95, v51
	v_subrev_u32_e32 v51, 41, v184
	s_nop 0
	v_cndmask_b32_e32 v115, v199, v103, vcc
	v_cmp_gt_u32_e32 vcc, s95, v52
	v_subrev_u32_e32 v52, 40, v184
	s_nop 0
	v_cndmask_b32_e32 v116, v199, v102, vcc
	v_cmp_gt_u32_e32 vcc, s95, v51
	v_add_u32_e32 v51, -11, v184
	s_nop 0
	v_cndmask_b32_e32 v57, v199, v119, vcc
	v_cmp_gt_u32_e32 vcc, s95, v52
	v_add_u32_e32 v52, -10, v184
	s_nop 0
	v_cndmask_b32_e32 v60, v199, v118, vcc
	v_cmp_gt_u32_e32 vcc, s95, v51
	v_subrev_u32_e32 v51, 43, v184
	s_nop 0
	v_cndmask_b32_e32 v117, v199, v105, vcc
	v_cmp_gt_u32_e32 vcc, s95, v52
	v_subrev_u32_e32 v52, 42, v184
	s_nop 0
	v_cndmask_b32_e32 v118, v199, v104, vcc
	v_cmp_gt_u32_e32 vcc, s95, v51
	v_subrev_u32_e32 v51, 17, v184
	s_nop 0
	v_cndmask_b32_e32 v61, v199, v121, vcc
	v_cmp_gt_u32_e32 vcc, s95, v52
	v_add_u32_e32 v52, -16, v184
	s_nop 0
	v_cndmask_b32_e32 v62, v199, v120, vcc
	v_cmp_gt_u32_e32 vcc, s95, v51
	v_subrev_u32_e32 v51, 49, v184
	s_nop 0
	v_cndmask_b32_e32 v100, v199, v107, vcc
	v_cmp_gt_u32_e32 vcc, s95, v52
	v_subrev_u32_e32 v52, 48, v184
	s_nop 0
	v_cndmask_b32_e32 v104, v199, v106, vcc
	v_cmp_gt_u32_e32 vcc, s95, v51
	s_nop 1
	v_cndmask_b32_e32 v51, v199, v123, vcc
	v_cmp_gt_u32_e32 vcc, s95, v52
	s_nop 1
	v_cndmask_b32_e32 v52, v199, v122, vcc
	v_cmp_gt_u32_e32 vcc, s95, v54
	v_subrev_u32_e32 v54, 51, v184
	s_nop 0
	v_cndmask_b32_e32 v102, v199, v109, vcc
	v_cmp_gt_u32_e32 vcc, s95, v55
	v_subrev_u32_e32 v55, 50, v184
	s_nop 0
	v_cndmask_b32_e32 v105, v199, v108, vcc
	v_cmp_gt_u32_e32 vcc, s95, v54
	s_nop 1
	v_cndmask_b32_e32 v54, v199, v125, vcc
	v_cmp_gt_u32_e32 vcc, s95, v55
	s_nop 1
	v_cndmask_b32_e32 v55, v199, v124, vcc
	v_cmp_gt_u32_e32 vcc, s95, v63
	v_subrev_u32_e32 v63, 57, v184
	s_nop 0
	v_cndmask_b32_e32 v103, v199, v111, vcc
	v_cmp_gt_u32_e32 vcc, s95, v64
	v_subrev_u32_e32 v64, 56, v184
	s_nop 0
	v_cndmask_b32_e32 v106, v199, v110, vcc
	v_cmp_gt_u32_e32 vcc, s95, v63
	s_nop 1
	v_cndmask_b32_e32 v63, v199, v127, vcc
	v_cmp_gt_u32_e32 vcc, s95, v64
	s_nop 1
	v_cndmask_b32_e32 v64, v199, v126, vcc
	v_cmp_gt_u32_e32 vcc, s95, v65
	v_subrev_u32_e32 v65, 59, v184
	s_nop 0
	v_cndmask_b32_e32 v107, v199, v113, vcc
	v_cmp_gt_u32_e32 vcc, s95, v98
	v_subrev_u32_e32 v98, 58, v184
	s_nop 0
	v_cndmask_b32_e32 v108, v199, v112, vcc
	v_cmp_gt_u32_e32 vcc, s95, v65
	s_nop 1
	v_cndmask_b32_e32 v65, v199, v129, vcc
	v_cmp_gt_u32_e32 vcc, s95, v98
	s_nop 1
	v_cndmask_b32_e32 v98, v199, v128, vcc
	v_cmp_nge_f32_e32 vcc, s9, v18
	s_cbranch_vccz .LBB0_338
; DI float ex2(float x) { return __builtin_amdgcn_exp2f(x); }
; DI float lg2(float x) { return __builtin_amdgcn_logf(x); }
; template <int MODE, int KS0, int NKS>
; DI void softmax_pv(const bf16x8 (&qf)[4], const u16* Ks, const u16* Vs, float& m, f32x16& ls, f32x16& o0, f32x16& o1,
;                    float sl2, int dl, bool need_mask, bool first, int r, int h, int rs, const int (&lo)[4]) {
;     ...
;   if (__any(first || !(ls[0] <= 1.0e12f))) {
;     float tmax = -INFINITY;
; #pragma unroll
;     for (int i = 0; i < 16; ++i) tmax = fmaxf(tmax, fmaxf(s0[i], s1[i]));
;     tmax = fmaxf(tmax, shx(tmax, r + 32 * h));
;     const float lref = (ls[0] > 1.f) ? lg2(ls[0]) : 0.f;
;     const float delta = first ? tmax : fmaxf(fmaxf(tmax, lref), 0.f);
;     m += delta;
;     const float alpha = ex2(-delta);
; #pragma unroll
;     for (int e = 0; e < 16; ++e) { o0[e] *= alpha; o1[e] *= alpha; ls[e] *= alpha; }
; #pragma unroll
;     for (int i = 0; i < 16; ++i) { s0[i] -= delta; s1[i] -= delta; }
;   }
	v_max_f32_e32 v109, v58, v58
	v_max_f32_e32 v110, v134, v134
	v_max_f32_e32 v109, v110, v109
	v_max_f32_e32 v110, v53, v53
	v_max_f32_e32 v111, v99, v99
	v_max_f32_e32 v110, v111, v110
	s_mov_b32 s2, 0xff800000
	v_max3_f32 v109, v109, s2, v110
	v_max_f32_e32 v110, v59, v59
	v_max_f32_e32 v111, v114, v114
	v_max_f32_e32 v110, v111, v110
	v_max_f32_e32 v111, v56, v56
	v_max_f32_e32 v112, v101, v101
	v_max_f32_e32 v111, v112, v111
	v_max3_f32 v109, v109, v110, v111
	v_max_f32_e32 v110, v60, v60
	v_max_f32_e32 v111, v116, v116
	v_max_f32_e32 v110, v111, v110
	v_max_f32_e32 v111, v57, v57
	v_max_f32_e32 v112, v115, v115
	v_max_f32_e32 v111, v112, v111
	v_max3_f32 v109, v109, v110, v111
	v_max_f32_e32 v110, v62, v62
	v_max_f32_e32 v111, v118, v118
	v_max_f32_e32 v110, v111, v110
	v_max_f32_e32 v111, v61, v61
	v_max_f32_e32 v112, v117, v117
	v_max_f32_e32 v111, v112, v111
	v_max3_f32 v109, v109, v110, v111
	v_max_f32_e32 v110, v52, v52
	v_max_f32_e32 v111, v104, v104
	v_max_f32_e32 v110, v111, v110
	v_max_f32_e32 v111, v51, v51
	v_max_f32_e32 v112, v100, v100
	v_max_f32_e32 v111, v112, v111
	v_max3_f32 v109, v109, v110, v111
	v_max_f32_e32 v110, v55, v55
	v_max_f32_e32 v111, v105, v105
	v_max_f32_e32 v110, v111, v110
	v_max_f32_e32 v111, v54, v54
	v_max_f32_e32 v112, v102, v102
	v_max_f32_e32 v111, v112, v111
	v_max3_f32 v109, v109, v110, v111
	v_max_f32_e32 v110, v64, v64
	v_max_f32_e32 v111, v106, v106
	v_max_f32_e32 v110, v111, v110
	v_max_f32_e32 v111, v63, v63
	v_max_f32_e32 v112, v103, v103
	v_max_f32_e32 v111, v112, v111
	v_max3_f32 v109, v109, v110, v111
	v_max_f32_e32 v110, v98, v98
	v_max_f32_e32 v111, v108, v108
	v_max_f32_e32 v110, v111, v110
	v_max_f32_e32 v111, v65, v65
	v_max_f32_e32 v112, v107, v107
	v_max_f32_e32 v111, v112, v111
	v_max3_f32 v109, v109, v110, v111
	ds_bpermute_b32 v110, v185, v109
	v_log_f32_e32 v111, v18
	v_cmp_lt_f32_e32 vcc, 1.0, v18
	s_waitcnt lgkmcnt(0)
	v_max_f32_e32 v110, v110, v110
	v_max_f32_e32 v109, v109, v110
	v_cndmask_b32_e32 v110, 0, v111, vcc
	v_max3_f32 v109, v109, v110, 0
	v_exp_f32_e64 v110, -v109
	v_sub_f32_e32 v134, v134, v109
	v_sub_f32_e32 v99, v99, v109
	v_sub_f32_e32 v114, v114, v109
	v_mul_f32_e32 v96, v96, v110
	v_mul_f32_e32 v97, v97, v110
	v_mul_f32_e32 v94, v94, v110
	v_mul_f32_e32 v95, v95, v110
	v_mul_f32_e32 v92, v92, v110
	v_mul_f32_e32 v93, v93, v110
	v_mul_f32_e32 v90, v90, v110
	v_mul_f32_e32 v91, v91, v110
	v_mul_f32_e32 v88, v88, v110
	v_mul_f32_e32 v89, v89, v110
	v_mul_f32_e32 v86, v86, v110
	v_mul_f32_e32 v87, v87, v110
	v_mul_f32_e32 v84, v84, v110
	v_mul_f32_e32 v85, v85, v110
	v_mul_f32_e32 v82, v82, v110
	v_mul_f32_e32 v83, v83, v110
	v_mul_f32_e32 v16, v16, v110
	v_mul_f32_e32 v17, v17, v110
	v_mul_f32_e32 v14, v14, v110
	v_mul_f32_e32 v15, v15, v110
	v_mul_f32_e32 v12, v12, v110
	v_mul_f32_e32 v13, v13, v110
	v_mul_f32_e32 v10, v10, v110
	v_mul_f32_e32 v11, v11, v110
	v_mul_f32_e32 v8, v8, v110
	v_mul_f32_e32 v9, v9, v110
	v_mul_f32_e32 v6, v6, v110
	v_mul_f32_e32 v7, v7, v110
	v_mul_f32_e32 v4, v4, v110
	v_mul_f32_e32 v5, v5, v110
	v_mul_f32_e32 v2, v2, v110
	v_mul_f32_e32 v3, v3, v110
	v_mul_f32_e32 v32, v32, v110
	v_mul_f32_e32 v33, v33, v110
	v_mul_f32_e32 v30, v30, v110
	v_mul_f32_e32 v31, v31, v110
	v_mul_f32_e32 v28, v28, v110
	v_mul_f32_e32 v29, v29, v110
	v_mul_f32_e32 v26, v26, v110
	v_mul_f32_e32 v27, v27, v110
	v_mul_f32_e32 v24, v24, v110
	v_mul_f32_e32 v25, v25, v110
	v_mul_f32_e32 v22, v22, v110
	v_mul_f32_e32 v23, v23, v110
	v_mul_f32_e32 v20, v20, v110
	v_mul_f32_e32 v21, v21, v110
	v_mul_f32_e32 v18, v18, v110
	v_mul_f32_e32 v19, v19, v110
	v_sub_f32_e32 v101, v101, v109
	v_sub_f32_e32 v116, v116, v109
	v_sub_f32_e32 v115, v115, v109
	v_sub_f32_e32 v118, v118, v109
	v_sub_f32_e32 v117, v117, v109
	v_sub_f32_e32 v104, v104, v109
	v_sub_f32_e32 v100, v100, v109
	v_sub_f32_e32 v105, v105, v109
	v_sub_f32_e32 v102, v102, v109
	v_sub_f32_e32 v106, v106, v109
	v_sub_f32_e32 v103, v103, v109
	v_sub_f32_e32 v108, v108, v109
	v_sub_f32_e32 v107, v107, v109
	v_sub_f32_e32 v58, v58, v109
	v_sub_f32_e32 v53, v53, v109
	v_sub_f32_e32 v59, v59, v109
	v_sub_f32_e32 v56, v56, v109
	v_sub_f32_e32 v60, v60, v109
	v_sub_f32_e32 v57, v57, v109
	v_sub_f32_e32 v62, v62, v109
	v_sub_f32_e32 v61, v61, v109
	v_sub_f32_e32 v52, v52, v109
	v_sub_f32_e32 v51, v51, v109
	v_sub_f32_e32 v55, v55, v109
	v_sub_f32_e32 v54, v54, v109
	v_sub_f32_e32 v64, v64, v109
	v_sub_f32_e32 v63, v63, v109
	v_sub_f32_e32 v98, v98, v109
	v_sub_f32_e32 v65, v65, v109
